# GEMM loop: F1 fragment reads interleaved into MFMA gaps; DA epilogue sub-LN weights prefetched in two batches; mlstm ctx chunk staging loads batched
# speedup vs baseline: 1.0852x; 1.0103x over previous
.Lg92_loop:
	v_add_u32_e32 v136, s34, v134
	v_add_u32_e32 v137, s34, v135
	s_add_i32 s9, s9, 1
	s_add_u32 s73, s34, 0x6000
	s_cmp_lt_u32 s73, 0x12000
	s_cselect_b32 s73, s73, 0
	v_add_u32_e32 v138, s73, v132
	v_add_u32_e32 v139, s73, v133
	s_waitcnt lgkmcnt(0)
	v_mfma_f32_32x32x16_bf16 v[114:129], v[162:165], v[228:231], v[114:129]
	ds_read_b128 v[166:169], v136 offset:0
	ds_read_b128 v[232:235], v137 offset:0
	s_add_i32 s14, s9, 2
	s_lshl_b64 s[12:13], s[14:15], 14
	v_lshl_add_u64 v[244:245], v[154:155], 0, s[12:13]
	v_mfma_f32_32x32x16_bf16 v[98:113], v[162:165], v[236:239], v[98:113]
	ds_read_b128 v[240:243], v137 offset:2048
	ds_read_b128 v[208:211], v136 offset:2048
	s_add_u32 s12, s12, 0x1000
	s_addc_u32 s13, s13, 0
	v_lshl_add_u64 v[246:247], v[154:155], 0, s[12:13]
	v_mfma_f32_32x32x16_bf16 v[82:97], v[204:207], v[228:231], v[82:97]
	ds_read_b128 v[216:219], v136 offset:4096
	ds_read_b128 v[224:227], v136 offset:6144
	s_add_u32 s12, s12, 0x1000
	s_addc_u32 s13, s13, 0
	v_lshl_add_u64 v[248:249], v[154:155], 0, s[12:13]
	v_mfma_f32_32x32x16_bf16 v[66:81], v[204:207], v[236:239], v[66:81]
	s_add_u32 s12, s12, 0x1000
	s_addc_u32 s13, s13, 0
	v_lshl_add_u64 v[140:141], v[154:155], 0, s[12:13]
	v_mfma_f32_32x32x16_bf16 v[50:65], v[212:215], v[228:231], v[50:65]
	s_lshl_b64 s[12:13], s[14:15], 13
	v_lshl_add_u64 v[142:143], v[156:157], 0, s[12:13]
	v_mfma_f32_32x32x16_bf16 v[34:49], v[212:215], v[236:239], v[34:49]
	s_add_u32 s12, s12, 0x1000
	s_addc_u32 s13, s13, 0
	v_lshl_add_u64 v[144:145], v[156:157], 0, s[12:13]
	v_mfma_f32_32x32x16_bf16 v[18:33], v[220:223], v[228:231], v[18:33]
	v_mfma_f32_32x32x16_bf16 v[2:17], v[220:223], v[236:239], v[2:17]
	s_waitcnt vmcnt(6) lgkmcnt(0)
	s_barrier
	s_add_u32 m0, s34, s72
	v_mfma_f32_32x32x16_bf16 v[114:129], v[166:169], v[232:235], v[114:129]
	global_load_lds_dwordx4 v[244:245], off
	ds_read_b128 v[162:165], v138 offset:0
	ds_read_b128 v[228:231], v139 offset:0
	s_add_u32 m0, m0, 0x1000
	v_mfma_f32_32x32x16_bf16 v[98:113], v[166:169], v[240:243], v[98:113]
	global_load_lds_dwordx4 v[246:247], off
	ds_read_b128 v[236:239], v139 offset:2048
	ds_read_b128 v[204:207], v138 offset:2048
	s_add_u32 m0, m0, 0x1000
	v_mfma_f32_32x32x16_bf16 v[82:97], v[208:211], v[232:235], v[82:97]
	global_load_lds_dwordx4 v[248:249], off
	ds_read_b128 v[212:215], v138 offset:4096
	ds_read_b128 v[220:223], v138 offset:6144
	s_add_u32 m0, m0, 0x1000
	v_mfma_f32_32x32x16_bf16 v[66:81], v[208:211], v[240:243], v[66:81]
	global_load_lds_dwordx4 v[140:141], off
	s_add_u32 m0, m0, 0x1000
	v_mfma_f32_32x32x16_bf16 v[50:65], v[216:219], v[232:235], v[50:65]
	global_load_lds_dwordx4 v[142:143], off
	s_add_u32 m0, m0, 0x1000
	v_mfma_f32_32x32x16_bf16 v[34:49], v[216:219], v[240:243], v[34:49]
	global_load_lds_dwordx4 v[144:145], off
	v_mfma_f32_32x32x16_bf16 v[18:33], v[224:227], v[232:235], v[18:33]
	v_mfma_f32_32x32x16_bf16 v[2:17], v[224:227], v[240:243], v[2:17]
	s_mov_b32 s34, s73
	s_cmp_lg_u32 s9, 29
	s_cbranch_scc1 .Lg92_loop
	v_add_u32_e32 v136, s34, v134
	v_add_u32_e32 v137, s34, v135
	s_add_i32 s9, s9, 1
	s_add_u32 s73, s34, 0x6000
	s_cmp_lt_u32 s73, 0x12000
	s_cselect_b32 s73, s73, 0
	v_add_u32_e32 v138, s73, v132
	v_add_u32_e32 v139, s73, v133
	s_waitcnt lgkmcnt(0)
	v_mfma_f32_32x32x16_bf16 v[114:129], v[162:165], v[228:231], v[114:129]
	ds_read_b128 v[166:169], v136 offset:0
	ds_read_b128 v[232:235], v137 offset:0
	v_mfma_f32_32x32x16_bf16 v[98:113], v[162:165], v[236:239], v[98:113]
	ds_read_b128 v[240:243], v137 offset:2048
	ds_read_b128 v[208:211], v136 offset:2048
	v_mfma_f32_32x32x16_bf16 v[82:97], v[204:207], v[228:231], v[82:97]
	ds_read_b128 v[216:219], v136 offset:4096
	ds_read_b128 v[224:227], v136 offset:6144
	v_mfma_f32_32x32x16_bf16 v[66:81], v[204:207], v[236:239], v[66:81]
	v_mfma_f32_32x32x16_bf16 v[50:65], v[212:215], v[228:231], v[50:65]
	v_mfma_f32_32x32x16_bf16 v[34:49], v[212:215], v[236:239], v[34:49]
	v_mfma_f32_32x32x16_bf16 v[18:33], v[220:223], v[228:231], v[18:33]
	v_mfma_f32_32x32x16_bf16 v[2:17], v[220:223], v[236:239], v[2:17]
	s_waitcnt vmcnt(6) lgkmcnt(0)
	s_barrier
	v_mfma_f32_32x32x16_bf16 v[114:129], v[166:169], v[232:235], v[114:129]
	ds_read_b128 v[162:165], v138 offset:0
	ds_read_b128 v[228:231], v139 offset:0
	v_mfma_f32_32x32x16_bf16 v[98:113], v[166:169], v[240:243], v[98:113]
	ds_read_b128 v[236:239], v139 offset:2048
	ds_read_b128 v[204:207], v138 offset:2048
	v_mfma_f32_32x32x16_bf16 v[82:97], v[208:211], v[232:235], v[82:97]
	ds_read_b128 v[212:215], v138 offset:4096
	ds_read_b128 v[220:223], v138 offset:6144
	v_mfma_f32_32x32x16_bf16 v[66:81], v[208:211], v[240:243], v[66:81]
	v_mfma_f32_32x32x16_bf16 v[50:65], v[216:219], v[232:235], v[50:65]
	v_mfma_f32_32x32x16_bf16 v[34:49], v[216:219], v[240:243], v[34:49]
	v_mfma_f32_32x32x16_bf16 v[18:33], v[224:227], v[232:235], v[18:33]
	v_mfma_f32_32x32x16_bf16 v[2:17], v[224:227], v[240:243], v[2:17]
	s_mov_b32 s34, s73
	v_add_u32_e32 v136, s34, v134
	v_add_u32_e32 v137, s34, v135
	s_add_i32 s9, s9, 1
	s_add_u32 s73, s34, 0x6000
	s_cmp_lt_u32 s73, 0x12000
	s_cselect_b32 s73, s73, 0
	v_add_u32_e32 v138, s73, v132
	v_add_u32_e32 v139, s73, v133
	s_waitcnt lgkmcnt(0)
	v_mfma_f32_32x32x16_bf16 v[114:129], v[162:165], v[228:231], v[114:129]
	ds_read_b128 v[166:169], v136 offset:0
	ds_read_b128 v[232:235], v137 offset:0
	v_mfma_f32_32x32x16_bf16 v[98:113], v[162:165], v[236:239], v[98:113]
	ds_read_b128 v[240:243], v137 offset:2048
	ds_read_b128 v[208:211], v136 offset:2048
	v_mfma_f32_32x32x16_bf16 v[82:97], v[204:207], v[228:231], v[82:97]
	ds_read_b128 v[216:219], v136 offset:4096
	ds_read_b128 v[224:227], v136 offset:6144
	v_mfma_f32_32x32x16_bf16 v[66:81], v[204:207], v[236:239], v[66:81]
	v_mfma_f32_32x32x16_bf16 v[50:65], v[212:215], v[228:231], v[50:65]
	v_mfma_f32_32x32x16_bf16 v[34:49], v[212:215], v[236:239], v[34:49]
	v_mfma_f32_32x32x16_bf16 v[18:33], v[220:223], v[228:231], v[18:33]
	v_mfma_f32_32x32x16_bf16 v[2:17], v[220:223], v[236:239], v[2:17]
	s_waitcnt vmcnt(0) lgkmcnt(0)
	s_barrier
	v_mfma_f32_32x32x16_bf16 v[114:129], v[166:169], v[232:235], v[114:129]
	ds_read_b128 v[162:165], v138 offset:0
	ds_read_b128 v[228:231], v139 offset:0
	v_mfma_f32_32x32x16_bf16 v[98:113], v[166:169], v[240:243], v[98:113]
	ds_read_b128 v[236:239], v139 offset:2048
	ds_read_b128 v[204:207], v138 offset:2048
	v_mfma_f32_32x32x16_bf16 v[82:97], v[208:211], v[232:235], v[82:97]
	ds_read_b128 v[212:215], v138 offset:4096
	ds_read_b128 v[220:223], v138 offset:6144
	v_mfma_f32_32x32x16_bf16 v[66:81], v[208:211], v[240:243], v[66:81]
	v_mfma_f32_32x32x16_bf16 v[50:65], v[216:219], v[232:235], v[50:65]
	v_mfma_f32_32x32x16_bf16 v[34:49], v[216:219], v[240:243], v[34:49]
	v_mfma_f32_32x32x16_bf16 v[18:33], v[224:227], v[232:235], v[18:33]
	v_mfma_f32_32x32x16_bf16 v[2:17], v[224:227], v[240:243], v[2:17]
	s_mov_b32 s34, s73
	v_add_u32_e32 v136, s34, v134
	v_add_u32_e32 v137, s34, v135
	s_add_i32 s9, s9, 1
	s_waitcnt lgkmcnt(0)
	v_mfma_f32_32x32x16_bf16 v[114:129], v[162:165], v[228:231], v[114:129]
	ds_read_b128 v[166:169], v136 offset:0
	ds_read_b128 v[232:235], v137 offset:0
	v_mfma_f32_32x32x16_bf16 v[98:113], v[162:165], v[236:239], v[98:113]
	ds_read_b128 v[240:243], v137 offset:2048
	ds_read_b128 v[208:211], v136 offset:2048
	v_mfma_f32_32x32x16_bf16 v[82:97], v[204:207], v[228:231], v[82:97]
	ds_read_b128 v[216:219], v136 offset:4096
	ds_read_b128 v[224:227], v136 offset:6144
	v_mfma_f32_32x32x16_bf16 v[66:81], v[204:207], v[236:239], v[66:81]
	v_mfma_f32_32x32x16_bf16 v[50:65], v[212:215], v[228:231], v[50:65]
	v_mfma_f32_32x32x16_bf16 v[34:49], v[212:215], v[236:239], v[34:49]
	v_mfma_f32_32x32x16_bf16 v[18:33], v[220:223], v[228:231], v[18:33]
	v_mfma_f32_32x32x16_bf16 v[2:17], v[220:223], v[236:239], v[2:17]
	s_waitcnt lgkmcnt(0)
	v_mfma_f32_32x32x16_bf16 v[114:129], v[166:169], v[232:235], v[114:129]
	v_mfma_f32_32x32x16_bf16 v[98:113], v[166:169], v[240:243], v[98:113]
	v_mfma_f32_32x32x16_bf16 v[82:97], v[208:211], v[232:235], v[82:97]
	v_mfma_f32_32x32x16_bf16 v[66:81], v[208:211], v[240:243], v[66:81]
	v_mfma_f32_32x32x16_bf16 v[50:65], v[216:219], v[232:235], v[50:65]
	v_mfma_f32_32x32x16_bf16 v[34:49], v[216:219], v[240:243], v[34:49]
	v_mfma_f32_32x32x16_bf16 v[18:33], v[224:227], v[232:235], v[18:33]
	v_mfma_f32_32x32x16_bf16 v[2:17], v[224:227], v[240:243], v[2:17]
	s_mov_b32 s14, 31
	s_lshl_b64 s[12:13], s[14:15], 13
	s_movk_i32 s34, 0x7800
	s_movk_i32 s72, 0x6000
	s_mov_b32 s73, 0xc000
	v_mov_b32_e32 v0, v171
	s_barrier
	s_waitcnt vmcnt(4)
	v_lshrrev_b32_e32 v130, 1, v0
	v_and_b32_e32 v130, 0xfffffc0, v130
	v_lshrrev_b32_e32 v131, 3, v0
	v_and_or_b32 v130, v131, 4, v130
	v_and_b32_e32 v0, 0x5f, v0
	v_mul_lo_u32 v130, v130, s53
	v_lshl_add_u32 v0, v0, 2, v130
	s_barrier
	ds_write2_b32 v0, v114, v98 offset1:32
	ds_write2_b32 v0, v115, v99 offset0:132 offset1:164
	v_add_u32_e32 v98, 0x400, v0
	ds_write2_b32 v98, v116, v100 offset0:8 offset1:40
	ds_write2_b32 v98, v117, v101 offset0:140 offset1:172
	v_add_u32_e32 v98, 0x1000, v0
	ds_write2_b32 v98, v118, v102 offset0:32 offset1:64
	ds_write2_b32 v98, v119, v103 offset0:164 offset1:196
	v_add_u32_e32 v98, 0x1400, v0
	ds_write2_b32 v98, v120, v104 offset0:40 offset1:72
	ds_write2_b32 v98, v121, v105 offset0:172 offset1:204
	v_add_u32_e32 v98, 0x2000, v0
	ds_write2_b32 v98, v122, v106 offset0:64 offset1:96
	ds_write2_b32 v98, v123, v107 offset0:196 offset1:228
	v_add_u32_e32 v98, 0x2400, v0
	ds_write2_b32 v98, v124, v108 offset0:72 offset1:104
	ds_write2_b32 v98, v125, v109 offset0:204 offset1:236
	v_add_u32_e32 v98, 0x3000, v0
	ds_write2_b32 v98, v126, v110 offset0:96 offset1:128
	v_add_u32_e32 v98, 0x3200, v0
	ds_write2_b32 v98, v127, v111 offset0:100 offset1:132
	v_add_u32_e32 v98, 0x3400, v0
	ds_write2_b32 v98, v128, v112 offset0:104 offset1:136
	v_add_u32_e32 v98, 0x3600, v0
	ds_write2_b32 v98, v129, v113 offset0:108 offset1:140
	v_add_u32_e32 v98, 0x4000, v0
	ds_write2_b32 v98, v82, v66 offset0:128 offset1:160
	v_add_u32_e32 v66, 0x4400, v0
	ds_write2_b32 v66, v83, v67 offset0:4 offset1:36
	ds_write2_b32 v66, v84, v68 offset0:136 offset1:168
	v_add_u32_e32 v66, 0x4800, v0
	ds_write2_b32 v66, v85, v69 offset0:12 offset1:44
	v_add_u32_e32 v66, 0x5000, v0
	ds_write2_b32 v66, v86, v70 offset0:160 offset1:192
	v_add_u32_e32 v66, 0x5400, v0
	ds_write2_b32 v66, v87, v71 offset0:36 offset1:68
	ds_write2_b32 v66, v88, v72 offset0:168 offset1:200
	v_add_u32_e32 v66, 0x5800, v0
	ds_write2_b32 v66, v89, v73 offset0:44 offset1:76
	v_add_u32_e32 v66, 0x6000, v0
	ds_write2_b32 v66, v90, v74 offset0:192 offset1:224
	v_add_u32_e32 v66, 0x6400, v0
	ds_write2_b32 v66, v91, v75 offset0:68 offset1:100
	ds_write2_b32 v66, v92, v76 offset0:200 offset1:232
	v_add_u32_e32 v66, 0x6800, v0
	ds_write2_b32 v66, v93, v77 offset0:76 offset1:108
	v_add_u32_e32 v66, 0x7200, v0
	ds_write2_b32 v66, v94, v78 offset0:96 offset1:128
	v_add_u32_e32 v66, 0x7400, v0
	ds_write2_b32 v66, v95, v79 offset0:100 offset1:132
	v_add_u32_e32 v66, 0x7600, v0
	v_add_u32_e32 v0, 0x7800, v0
	v_mov_b32_e32 v74, v171
	ds_write2_b32 v66, v96, v80 offset0:104 offset1:136
	ds_write2_b32 v0, v97, v81 offset0:108 offset1:140
	s_waitcnt lgkmcnt(0)
	s_barrier
	s_lshl_b32 s8, s8, 7
	v_lshlrev_b32_e32 v75, 3, v74
	v_and_b32_e32 v0, 0x78, v75
	v_or_b32_e32 v0, s8, v0
	v_lshl_add_u64 v[70:71], v[0:1], 2, s[6:7]
	global_load_dwordx4 v[66:69], v[70:71], off
	s_nop 0
	global_load_dwordx4 v[70:73], v[70:71], off offset:16
	v_ashrrev_i32_e32 v76, 4, v74
	v_lshrrev_b32_e32 v77, 5, v0
	v_and_b32_e32 v0, 24, v75
	v_mul_lo_u32 v75, v76, s53
	v_and_b32_e32 v74, 15, v74
	v_readlane_b32 s0, v252, 46
	s_lshl_b32 s9, s11, 8
	v_lshl_add_u32 v78, v74, 5, v75
	v_lshlrev_b32_e32 v79, 1, v76
	s_mov_b32 s11, 0
	v_lshlrev_b32_e32 v74, 1, v0
	v_readlane_b32 s1, v252, 47
	s_waitcnt vmcnt(0)

.LBB0_283:
	s_or_b64 exec, exec, s[4:5]
	v_cmp_gt_i32_e32 vcc, 2, v163
	s_waitcnt lgkmcnt(0)
	s_barrier
	s_and_saveexec_b64 s[4:5], vcc
	s_xor_b64 s[4:5], exec, s[4:5]
	s_mov_b32 s41, s2
	s_cbranch_execz .LBB0_285
	v_readlane_b32 s0, v254, 35
	v_readlane_b32 s1, v254, 36
	v_readlane_b32 s2, v254, 37
	s_mov_b32 s7, s15
	v_readlane_b32 s3, v254, 38
	s_nop 1
	global_load_dword v0, v1, s[0:1]
	ds_read2st64_b32 v[10:11], v8 offset1:2
	ds_read2st64_b32 v[40:41], v8 offset0:4 offset1:6
	ds_read2st64_b32 v[48:49], v8 offset0:8 offset1:10
	ds_read2st64_b32 v[108:109], v8 offset0:12 offset1:14
	ds_read2st64_b32 v[120:121], v8 offset0:16 offset1:18
	ds_read2st64_b32 v[114:115], v8 offset0:20 offset1:22
	ds_read2st64_b32 v[132:133], v8 offset0:24 offset1:26
	ds_read2st64_b32 v[126:127], v8 offset0:28 offset1:30
	ds_read2st64_b32 v[134:135], v8 offset0:32 offset1:34
	ds_read2st64_b32 v[136:137], v8 offset0:36 offset1:38
	ds_read2st64_b32 v[128:129], v8 offset0:40 offset1:42
	s_waitcnt vmcnt(1)
	ds_read2st64_b32 v[138:139], v8 offset0:44 offset1:46
	ds_read2st64_b32 v[122:123], v8 offset0:48 offset1:50
	ds_read2st64_b32 v[140:141], v8 offset0:52 offset1:54
	ds_read2st64_b32 v[116:117], v8 offset0:56 offset1:58
	ds_read2st64_b32 v[124:125], v8 offset0:60 offset1:62
	ds_read2st64_b32 v[16:17], v8 offset0:64 offset1:66
	ds_read2st64_b32 v[118:119], v8 offset0:68 offset1:70
	ds_read2st64_b32 v[14:15], v8 offset0:72 offset1:74
	ds_read2st64_b32 v[110:111], v8 offset0:76 offset1:78
	ds_read2st64_b32 v[32:33], v8 offset0:80 offset1:82
	ds_read2st64_b32 v[106:107], v8 offset0:84 offset1:86
	ds_read2st64_b32 v[90:91], v8 offset0:88 offset1:90
	ds_read2st64_b32 v[98:99], v8 offset0:92 offset1:94
	ds_read2st64_b32 v[88:89], v8 offset0:96 offset1:98
	ds_read2st64_b32 v[96:97], v8 offset0:100 offset1:102
	ds_read2st64_b32 v[84:85], v8 offset0:104 offset1:106
	ds_read2st64_b32 v[92:93], v8 offset0:108 offset1:110
	ds_read2st64_b32 v[78:79], v8 offset0:112 offset1:114
	ds_read2st64_b32 v[86:87], v8 offset0:116 offset1:118
	ds_read2st64_b32 v[6:7], v8 offset0:120 offset1:122
	s_movk_i32 s0, 0xc00
	s_waitcnt vmcnt(0) lgkmcnt(0)
	v_pk_fma_f32 v[6:7], v[0:1], v[6:7], v[4:5] op_sel_hi:[0,1,1] neg_lo:[1,0,0] neg_hi:[1,0,0]
	ds_read2st64_b32 v[4:5], v8 offset0:124 offset1:126
	v_pk_fma_f32 v[80:81], v[0:1], v[10:11], v[80:81] op_sel_hi:[0,1,1] neg_lo:[1,0,0] neg_hi:[1,0,0]
	v_pk_fma_f32 v[40:41], v[0:1], v[40:41], v[100:101] op_sel_hi:[0,1,1] neg_lo:[1,0,0] neg_hi:[1,0,0]
	v_pk_mul_f32 v[104:105], v[80:81], v[80:81]
	v_pk_mul_f32 v[102:103], v[40:41], v[40:41]
	s_waitcnt lgkmcnt(0)
	v_pk_fma_f32 v[8:9], v[0:1], v[4:5], v[2:3] op_sel_hi:[0,1,1] neg_lo:[1,0,0] neg_hi:[1,0,0]
	v_mov_b64_e32 v[2:3], s[64:65]
	v_mad_u64_u32 v[2:3], s[8:9], v149, s0, v[2:3]
	v_lshl_add_u64 v[112:113], v[2:3], 0, s[6:7]
	global_load_dwordx4 v[218:221], v146, s[2:3] offset:0
	global_load_dwordx4 v[222:225], v146, s[2:3] offset:32
	global_load_dwordx4 v[226:229], v146, s[2:3] offset:64
	global_load_dwordx4 v[230:233], v146, s[2:3] offset:96
	global_load_dwordx4 v[234:237], v146, s[2:3] offset:128
	global_load_dwordx4 v[238:241], v146, s[2:3] offset:160
	global_load_dwordx4 v[242:245], v146, s[2:3] offset:192
	global_load_dwordx4 v[246:249], v146, s[2:3] offset:224
	v_pk_fma_f32 v[76:77], v[0:1], v[108:109], v[76:77] op_sel_hi:[0,1,1] neg_lo:[1,0,0] neg_hi:[1,0,0]
	v_pk_fma_f32 v[100:101], v[0:1], v[48:49], v[70:71] op_sel_hi:[0,1,1] neg_lo:[1,0,0] neg_hi:[1,0,0]
	v_pk_fma_f32 v[70:71], v[0:1], v[114:115], v[82:83] op_sel_hi:[0,1,1] neg_lo:[1,0,0] neg_hi:[1,0,0]
	v_pk_fma_f32 v[82:83], v[0:1], v[120:121], v[66:67] op_sel_hi:[0,1,1] neg_lo:[1,0,0] neg_hi:[1,0,0]
	v_pk_fma_f32 v[66:67], v[0:1], v[126:127], v[72:73] op_sel_hi:[0,1,1] neg_lo:[1,0,0] neg_hi:[1,0,0]
	v_pk_fma_f32 v[72:73], v[0:1], v[132:133], v[68:69] op_sel_hi:[0,1,1] neg_lo:[1,0,0] neg_hi:[1,0,0]
	v_pk_fma_f32 v[58:59], v[0:1], v[136:137], v[58:59] op_sel_hi:[0,1,1] neg_lo:[1,0,0] neg_hi:[1,0,0]
	v_pk_fma_f32 v[68:69], v[0:1], v[134:135], v[60:61] op_sel_hi:[0,1,1] neg_lo:[1,0,0] neg_hi:[1,0,0]
	v_pk_fma_f32 v[48:49], v[0:1], v[138:139], v[94:95] op_sel_hi:[0,1,1] neg_lo:[1,0,0] neg_hi:[1,0,0]
	v_pk_fma_f32 v[60:61], v[0:1], v[128:129], v[54:55] op_sel_hi:[0,1,1] neg_lo:[1,0,0] neg_hi:[1,0,0]
	v_pk_fma_f32 v[44:45], v[0:1], v[140:141], v[44:45] op_sel_hi:[0,1,1] neg_lo:[1,0,0] neg_hi:[1,0,0]
	v_pk_fma_f32 v[54:55], v[0:1], v[122:123], v[38:39] op_sel_hi:[0,1,1] neg_lo:[1,0,0] neg_hi:[1,0,0]
	v_pk_fma_f32 v[38:39], v[0:1], v[124:125], v[74:75] op_sel_hi:[0,1,1] neg_lo:[1,0,0] neg_hi:[1,0,0]
	v_pk_fma_f32 v[46:47], v[0:1], v[116:117], v[46:47] op_sel_hi:[0,1,1] neg_lo:[1,0,0] neg_hi:[1,0,0]
	v_pk_fma_f32 v[34:35], v[0:1], v[118:119], v[34:35] op_sel_hi:[0,1,1] neg_lo:[1,0,0] neg_hi:[1,0,0]
	v_pk_fma_f32 v[42:43], v[0:1], v[16:17], v[42:43] op_sel_hi:[0,1,1] neg_lo:[1,0,0] neg_hi:[1,0,0]
	v_pk_fma_f32 v[16:17], v[0:1], v[110:111], v[64:65] op_sel_hi:[0,1,1] neg_lo:[1,0,0] neg_hi:[1,0,0]
	v_pk_fma_f32 v[36:37], v[0:1], v[14:15], v[36:37] op_sel_hi:[0,1,1] neg_lo:[1,0,0] neg_hi:[1,0,0]
	v_pk_fma_f32 v[14:15], v[0:1], v[106:107], v[56:57] op_sel_hi:[0,1,1] neg_lo:[1,0,0] neg_hi:[1,0,0]
	v_pk_fma_f32 v[32:33], v[0:1], v[32:33], v[50:51] op_sel_hi:[0,1,1] neg_lo:[1,0,0] neg_hi:[1,0,0]
	v_pk_fma_f32 v[30:31], v[0:1], v[98:99], v[30:31] op_sel_hi:[0,1,1] neg_lo:[1,0,0] neg_hi:[1,0,0]
	v_pk_fma_f32 v[50:51], v[0:1], v[90:91], v[24:25] op_sel_hi:[0,1,1] neg_lo:[1,0,0] neg_hi:[1,0,0]
	v_pk_fma_f32 v[24:25], v[0:1], v[96:97], v[28:29] op_sel_hi:[0,1,1] neg_lo:[1,0,0] neg_hi:[1,0,0]
	v_pk_fma_f32 v[28:29], v[0:1], v[88:89], v[22:23] op_sel_hi:[0,1,1] neg_lo:[1,0,0] neg_hi:[1,0,0]
	v_pk_fma_f32 v[22:23], v[0:1], v[92:93], v[26:27] op_sel_hi:[0,1,1] neg_lo:[1,0,0] neg_hi:[1,0,0]
	v_pk_fma_f32 v[20:21], v[0:1], v[84:85], v[20:21] op_sel_hi:[0,1,1] neg_lo:[1,0,0] neg_hi:[1,0,0]
	v_pk_fma_f32 v[12:13], v[0:1], v[86:87], v[12:13] op_sel_hi:[0,1,1] neg_lo:[1,0,0] neg_hi:[1,0,0]
	v_pk_fma_f32 v[18:19], v[0:1], v[78:79], v[18:19] op_sel_hi:[0,1,1] neg_lo:[1,0,0] neg_hi:[1,0,0]
	v_add_f32_e32 v0, v104, v105
	v_mov_b32_e32 v149, v1
	v_add_f32_e32 v0, v0, v102
	v_lshl_add_u64 v[10:11], v[112:113], 0, v[148:149]
	v_pk_mul_f32 v[112:113], v[100:101], v[100:101]
	v_add_f32_e32 v0, v0, v103
	v_add_f32_e32 v0, v0, v112
	v_pk_mul_f32 v[108:109], v[76:77], v[76:77]
	v_add_f32_e32 v0, v0, v113
	v_add_f32_e32 v0, v0, v108
	v_pk_mul_f32 v[120:121], v[82:83], v[82:83]
	v_add_f32_e32 v0, v0, v109
	v_add_f32_e32 v0, v0, v120
	v_pk_mul_f32 v[114:115], v[70:71], v[70:71]
	v_add_f32_e32 v0, v0, v121
	v_add_f32_e32 v0, v0, v114
	v_pk_mul_f32 v[132:133], v[72:73], v[72:73]
	v_add_f32_e32 v0, v0, v115
	v_add_f32_e32 v0, v0, v132
	v_pk_mul_f32 v[126:127], v[66:67], v[66:67]
	v_add_f32_e32 v0, v0, v133
	v_add_f32_e32 v0, v0, v126
	v_pk_mul_f32 v[134:135], v[68:69], v[68:69]
	v_add_f32_e32 v0, v0, v127
	v_add_f32_e32 v0, v0, v134
	v_pk_mul_f32 v[136:137], v[58:59], v[58:59]
	v_add_f32_e32 v0, v0, v135
	v_add_f32_e32 v0, v0, v136
	v_pk_mul_f32 v[128:129], v[60:61], v[60:61]
	v_add_f32_e32 v0, v0, v137
	v_add_f32_e32 v0, v0, v128
	v_pk_mul_f32 v[94:95], v[48:49], v[48:49]
	v_add_f32_e32 v0, v0, v129
	v_add_f32_e32 v0, v0, v94
	v_pk_mul_f32 v[122:123], v[54:55], v[54:55]
	v_add_f32_e32 v0, v0, v95
	v_add_f32_e32 v0, v0, v122
	v_pk_mul_f32 v[138:139], v[44:45], v[44:45]
	v_add_f32_e32 v0, v0, v123
	v_add_f32_e32 v0, v0, v138
	v_pk_mul_f32 v[116:117], v[46:47], v[46:47]
	v_add_f32_e32 v0, v0, v139
	v_add_f32_e32 v0, v0, v116
	v_pk_mul_f32 v[74:75], v[38:39], v[38:39]
	v_add_f32_e32 v0, v0, v117
	v_add_f32_e32 v0, v0, v74
	v_pk_mul_f32 v[124:125], v[42:43], v[42:43]
	v_add_f32_e32 v0, v0, v75
	v_add_f32_e32 v0, v0, v124
	v_pk_mul_f32 v[118:119], v[34:35], v[34:35]
	v_add_f32_e32 v0, v0, v125
	v_add_f32_e32 v0, v0, v118
	v_pk_mul_f32 v[110:111], v[36:37], v[36:37]
	v_add_f32_e32 v0, v0, v119
	v_add_f32_e32 v0, v0, v110
	v_pk_mul_f32 v[64:65], v[16:17], v[16:17]
	v_add_f32_e32 v0, v0, v111
	v_add_f32_e32 v0, v0, v64
	v_pk_mul_f32 v[106:107], v[32:33], v[32:33]
	v_add_f32_e32 v0, v0, v65
	v_add_f32_e32 v0, v0, v106
	v_pk_mul_f32 v[56:57], v[14:15], v[14:15]
	v_add_f32_e32 v0, v0, v107
	v_add_f32_e32 v0, v0, v56
	v_pk_mul_f32 v[90:91], v[50:51], v[50:51]
	v_add_f32_e32 v0, v0, v57
	v_add_f32_e32 v0, v0, v90
	v_pk_mul_f32 v[98:99], v[30:31], v[30:31]
	v_add_f32_e32 v0, v0, v91
	v_add_f32_e32 v0, v0, v98
	v_pk_mul_f32 v[88:89], v[28:29], v[28:29]
	v_add_f32_e32 v0, v0, v99
	v_add_f32_e32 v0, v0, v88
	v_pk_mul_f32 v[96:97], v[24:25], v[24:25]
	v_add_f32_e32 v0, v0, v89
	v_add_f32_e32 v0, v0, v96
	v_pk_mul_f32 v[84:85], v[20:21], v[20:21]
	v_add_f32_e32 v0, v0, v97
	v_add_f32_e32 v0, v0, v84
	v_pk_mul_f32 v[26:27], v[22:23], v[22:23]
	v_add_f32_e32 v0, v0, v85
	v_add_f32_e32 v0, v0, v26
	v_pk_mul_f32 v[78:79], v[18:19], v[18:19]
	v_add_f32_e32 v0, v0, v27
	v_add_f32_e32 v0, v0, v78
	v_pk_mul_f32 v[86:87], v[12:13], v[12:13]
	v_add_f32_e32 v0, v0, v79
	v_add_f32_e32 v0, v0, v86
	v_pk_mul_f32 v[52:53], v[6:7], v[6:7]
	v_add_f32_e32 v0, v0, v87
	v_add_f32_e32 v0, v0, v52
	v_pk_mul_f32 v[62:63], v[8:9], v[8:9]
	v_add_f32_e32 v0, v0, v53
	v_add_f32_e32 v0, v0, v62
	v_add_f32_e32 v0, v0, v63
	ds_bpermute_b32 v26, v130, v0
	s_mov_b32 s0, 0x800000
	s_waitcnt lgkmcnt(0)
	v_add_f32_e32 v0, v0, v26
	v_fmamk_f32 v0, v0, 0x3c000000, v177
	v_cmp_gt_f32_e32 vcc, s0, v0
	v_mul_f32_e32 v26, 0x4b800000, v0
	s_nop 0
	v_cndmask_b32_e32 v0, v0, v26, vcc
	v_rsq_f32_e32 v0, v0
	s_nop 0
	v_mul_f32_e32 v26, 0x45800000, v0
	v_cndmask_b32_e32 v0, v0, v26, vcc
	v_mul_f32_e32 v0, v151, v0
	v_pk_mul_f32 v[26:27], v[80:81], v[0:1] op_sel_hi:[1,0]
	v_pk_mul_f32 v[16:17], v[16:17], v[0:1] op_sel_hi:[1,0]
	s_waitcnt vmcnt(0)
	v_pk_mul_f32 v[2:3], v[218:219], v[26:27]
	v_pk_mul_f32 v[26:27], v[40:41], v[0:1] op_sel_hi:[1,0]
	v_cvt_pk_bf16_f32 v2, v2, v3
	v_pk_mul_f32 v[4:5], v[220:221], v[26:27]
	v_pk_mul_f32 v[26:27], v[100:101], v[0:1] op_sel_hi:[1,0]
	v_cvt_pk_bf16_f32 v3, v4, v5
	global_store_dwordx2 v[10:11], v[2:3], off
	v_pk_mul_f32 v[14:15], v[14:15], v[0:1] op_sel_hi:[1,0]
	v_pk_mul_f32 v[12:13], v[12:13], v[0:1] op_sel_hi:[1,0]
	v_pk_mul_f32 v[6:7], v[6:7], v[0:1] op_sel_hi:[1,0]
	v_pk_mul_f32 v[2:3], v[222:223], v[26:27]
	v_pk_mul_f32 v[26:27], v[76:77], v[0:1] op_sel_hi:[1,0]
	v_cvt_pk_bf16_f32 v2, v2, v3
	v_pk_mul_f32 v[4:5], v[224:225], v[26:27]
	v_pk_mul_f32 v[26:27], v[82:83], v[0:1] op_sel_hi:[1,0]
	v_cvt_pk_bf16_f32 v3, v4, v5
	global_store_dwordx2 v[10:11], v[2:3], off offset:16
	v_pk_mul_f32 v[2:3], v[226:227], v[26:27]
	v_pk_mul_f32 v[26:27], v[70:71], v[0:1] op_sel_hi:[1,0]
	v_cvt_pk_bf16_f32 v2, v2, v3
	v_pk_mul_f32 v[4:5], v[26:27], v[228:229]
	v_pk_mul_f32 v[26:27], v[72:73], v[0:1] op_sel_hi:[1,0]
	v_cvt_pk_bf16_f32 v3, v4, v5
	global_store_dwordx2 v[10:11], v[2:3], off offset:32
	v_pk_mul_f32 v[2:3], v[26:27], v[230:231]
	v_pk_mul_f32 v[26:27], v[66:67], v[0:1] op_sel_hi:[1,0]
	v_cvt_pk_bf16_f32 v2, v2, v3
	v_pk_mul_f32 v[4:5], v[26:27], v[232:233]
	v_pk_mul_f32 v[26:27], v[68:69], v[0:1] op_sel_hi:[1,0]
	v_cvt_pk_bf16_f32 v3, v4, v5
	global_store_dwordx2 v[10:11], v[2:3], off offset:48
	v_pk_mul_f32 v[2:3], v[26:27], v[234:235]
	v_pk_mul_f32 v[26:27], v[58:59], v[0:1] op_sel_hi:[1,0]
	v_cvt_pk_bf16_f32 v2, v2, v3
	v_pk_mul_f32 v[4:5], v[26:27], v[236:237]
	v_pk_mul_f32 v[26:27], v[60:61], v[0:1] op_sel_hi:[1,0]
	v_cvt_pk_bf16_f32 v3, v4, v5
	global_store_dwordx2 v[10:11], v[2:3], off offset:64
	v_pk_mul_f32 v[2:3], v[26:27], v[238:239]
	v_pk_mul_f32 v[26:27], v[48:49], v[0:1] op_sel_hi:[1,0]
	v_cvt_pk_bf16_f32 v2, v2, v3
	v_pk_mul_f32 v[4:5], v[26:27], v[240:241]
	v_pk_mul_f32 v[26:27], v[54:55], v[0:1] op_sel_hi:[1,0]
	v_cvt_pk_bf16_f32 v3, v4, v5
	global_store_dwordx2 v[10:11], v[2:3], off offset:80
	v_pk_mul_f32 v[2:3], v[26:27], v[242:243]
	v_pk_mul_f32 v[26:27], v[44:45], v[0:1] op_sel_hi:[1,0]
	v_cvt_pk_bf16_f32 v2, v2, v3
	v_pk_mul_f32 v[4:5], v[26:27], v[244:245]
	v_pk_mul_f32 v[26:27], v[46:47], v[0:1] op_sel_hi:[1,0]
	v_cvt_pk_bf16_f32 v3, v4, v5
	global_store_dwordx2 v[10:11], v[2:3], off offset:96
	v_pk_mul_f32 v[2:3], v[26:27], v[246:247]
	v_pk_mul_f32 v[26:27], v[38:39], v[0:1] op_sel_hi:[1,0]
	v_cvt_pk_bf16_f32 v2, v2, v3
	v_pk_mul_f32 v[4:5], v[26:27], v[248:249]
	v_pk_mul_f32 v[26:27], v[42:43], v[0:1] op_sel_hi:[1,0]
	v_cvt_pk_bf16_f32 v3, v4, v5
	global_store_dwordx2 v[10:11], v[2:3], off offset:112
	global_load_dwordx4 v[218:221], v146, s[2:3] offset:256
	global_load_dwordx4 v[222:225], v146, s[2:3] offset:288
	global_load_dwordx4 v[226:229], v146, s[2:3] offset:320
	global_load_dwordx4 v[230:233], v146, s[2:3] offset:352
	global_load_dwordx4 v[234:237], v146, s[2:3] offset:384
	global_load_dwordx4 v[238:241], v146, s[2:3] offset:416
	global_load_dwordx4 v[242:245], v146, s[2:3] offset:448
	global_load_dwordx4 v[246:249], v146, s[2:3] offset:480
	s_waitcnt vmcnt(0)
	v_pk_mul_f32 v[2:3], v[26:27], v[218:219]
	v_pk_mul_f32 v[26:27], v[34:35], v[0:1] op_sel_hi:[1,0]
	v_cvt_pk_bf16_f32 v2, v2, v3
	v_pk_mul_f32 v[4:5], v[26:27], v[220:221]
	v_pk_mul_f32 v[26:27], v[36:37], v[0:1] op_sel_hi:[1,0]
	v_cvt_pk_bf16_f32 v3, v4, v5
	global_store_dwordx2 v[10:11], v[2:3], off offset:128
	v_pk_mul_f32 v[2:3], v[26:27], v[222:223]
	v_pk_mul_f32 v[4:5], v[16:17], v[224:225]
	v_cvt_pk_bf16_f32 v2, v2, v3
	v_cvt_pk_bf16_f32 v3, v4, v5
	global_store_dwordx2 v[10:11], v[2:3], off offset:144
	v_pk_mul_f32 v[16:17], v[32:33], v[0:1] op_sel_hi:[1,0]
	v_pk_mul_f32 v[4:5], v[14:15], v[228:229]
	v_pk_mul_f32 v[2:3], v[16:17], v[226:227]
	v_pk_mul_f32 v[14:15], v[50:51], v[0:1] op_sel_hi:[1,0]
	v_cvt_pk_bf16_f32 v2, v2, v3
	v_cvt_pk_bf16_f32 v3, v4, v5
	global_store_dwordx2 v[10:11], v[2:3], off offset:160
	v_pk_mul_f32 v[2:3], v[14:15], v[230:231]
	v_pk_mul_f32 v[14:15], v[30:31], v[0:1] op_sel_hi:[1,0]
	v_cvt_pk_bf16_f32 v2, v2, v3
	v_pk_mul_f32 v[4:5], v[14:15], v[232:233]
	v_pk_mul_f32 v[14:15], v[28:29], v[0:1] op_sel_hi:[1,0]
	v_cvt_pk_bf16_f32 v3, v4, v5
	global_store_dwordx2 v[10:11], v[2:3], off offset:176
	v_pk_mul_f32 v[2:3], v[14:15], v[234:235]
	v_pk_mul_f32 v[14:15], v[24:25], v[0:1] op_sel_hi:[1,0]
	v_cvt_pk_bf16_f32 v2, v2, v3
	v_pk_mul_f32 v[4:5], v[14:15], v[236:237]
	v_pk_mul_f32 v[14:15], v[20:21], v[0:1] op_sel_hi:[1,0]
	v_cvt_pk_bf16_f32 v3, v4, v5
	global_store_dwordx2 v[10:11], v[2:3], off offset:192
	v_pk_mul_f32 v[2:3], v[14:15], v[238:239]
	v_pk_mul_f32 v[14:15], v[22:23], v[0:1] op_sel_hi:[1,0]
	v_cvt_pk_bf16_f32 v2, v2, v3
	v_pk_mul_f32 v[4:5], v[14:15], v[240:241]
	v_pk_mul_f32 v[14:15], v[18:19], v[0:1] op_sel_hi:[1,0]
	v_cvt_pk_bf16_f32 v3, v4, v5
	global_store_dwordx2 v[10:11], v[2:3], off offset:208
	v_pk_mul_f32 v[2:3], v[14:15], v[242:243]
	v_pk_mul_f32 v[4:5], v[12:13], v[244:245]
	v_cvt_pk_bf16_f32 v2, v2, v3
	v_cvt_pk_bf16_f32 v3, v4, v5
	global_store_dwordx2 v[10:11], v[2:3], off offset:224
	v_pk_mul_f32 v[2:3], v[6:7], v[246:247]
	v_pk_mul_f32 v[6:7], v[8:9], v[0:1] op_sel_hi:[1,0]
	v_cvt_pk_bf16_f32 v2, v2, v3
	v_pk_mul_f32 v[4:5], v[6:7], v[248:249]
	s_nop 0
	v_cvt_pk_bf16_f32 v3, v4, v5
	global_store_dwordx2 v[10:11], v[2:3], off offset:240

.LBB0_292:
	s_and_b64 s[6:7], s[42:43], exec
	s_cselect_b32 s8, s81, s50
	v_mov_b32_e32 v115, v171
	s_lshl_b32 s79, s8, 6
	s_add_i32 s9, s79, s80
	v_lshlrev_b32_e32 v76, 4, v115
	v_and_b32_e32 v0, 0xf0, v76
	v_ashrrev_i32_e32 v66, 4, v115
	v_lshl_add_u64 v[70:71], s[4:5], 0, v[0:1]
	v_add_u32_e32 v67, s9, v66
	v_mad_i64_i32 v[72:73], s[6:7], v67, s52, v[70:71]
	s_movk_i32 s0, 0x110
	s_waitcnt lgkmcnt(0)
	s_barrier
	v_add_u32_e32 v78, 0x100, v115
	v_add_u32_e32 v79, 0x200, v115
	v_add_u32_e32 v80, 0x300, v115
	v_and_b32_e32 v82, 63, v115
	global_load_dwordx4 v[218:221], v[72:73], off offset:2048
	global_load_dwordx4 v[222:225], v[72:73], off offset:3072
	v_ashrrev_i32_e32 v66, 4, v78
	v_add_u32_e32 v67, s9, v66
	v_mad_i64_i32 v[72:73], s[6:7], v67, s52, v[70:71]
	global_load_dwordx4 v[226:229], v[72:73], off offset:2048
	global_load_dwordx4 v[230:233], v[72:73], off offset:3072
	v_ashrrev_i32_e32 v66, 4, v79
	v_add_u32_e32 v67, s9, v66
	v_mad_i64_i32 v[72:73], s[6:7], v67, s52, v[70:71]
	global_load_dwordx4 v[234:237], v[72:73], off offset:2048
	global_load_dwordx4 v[238:241], v[72:73], off offset:3072
	v_ashrrev_i32_e32 v66, 4, v80
	v_add_u32_e32 v67, s9, v66
	v_mad_i64_i32 v[72:73], s[6:7], v67, s52, v[70:71]
	global_load_dwordx4 v[242:245], v[72:73], off offset:2048
	global_load_dwordx4 v[246:249], v[72:73], off offset:3072
	v_ashrrev_i32_e32 v66, 4, v115
	v_mad_u32_u24 v66, v66, s0, v0
	s_waitcnt vmcnt(7)
	ds_write_b128 v66, v[218:221]
	s_waitcnt vmcnt(6)
	ds_write_b128 v66, v[222:225] offset:17408
	v_ashrrev_i32_e32 v66, 4, v78
	v_mad_u32_u24 v66, v66, s0, v0
	s_waitcnt vmcnt(5)
	ds_write_b128 v66, v[226:229]
	s_waitcnt vmcnt(4)
	ds_write_b128 v66, v[230:233] offset:17408
	v_ashrrev_i32_e32 v66, 4, v79
	v_mad_u32_u24 v66, v66, s0, v0
	s_waitcnt vmcnt(3)
	ds_write_b128 v66, v[234:237]
	s_waitcnt vmcnt(2)
	ds_write_b128 v66, v[238:241] offset:17408
	v_ashrrev_i32_e32 v66, 4, v80
	v_mad_u32_u24 v66, v66, s0, v0
	s_waitcnt vmcnt(1)
	ds_write_b128 v66, v[242:245]
	s_waitcnt vmcnt(0)
	ds_write_b128 v66, v[246:249] offset:17408
	s_lshl_b32 s8, s8, 7
	s_add_u32 s6, s14, s8
	s_addc_u32 s7, s51, 0
	v_and_b32_e32 v0, 0x70, v76
	v_lshl_add_u64 v[70:71], s[6:7], 0, v[0:1]
	s_add_u32 s6, s68, s8
	s_addc_u32 s7, s69, 0
	v_lshl_add_u64 v[72:73], s[6:7], 0, v[0:1]
	v_ashrrev_i32_e32 v66, 3, v115
	v_ashrrev_i32_e32 v67, 31, v66
	v_lshlrev_b64 v[74:75], 9, v[66:67]
	v_lshl_add_u64 v[68:69], v[70:71], 0, v[74:75]
	global_load_dwordx4 v[218:221], v[68:69], off
	v_lshl_add_u64 v[68:69], v[72:73], 0, v[74:75]
	global_load_dwordx4 v[222:225], v[68:69], off
	v_ashrrev_i32_e32 v66, 3, v78
	v_ashrrev_i32_e32 v67, 31, v66
	v_lshlrev_b64 v[74:75], 9, v[66:67]
	v_lshl_add_u64 v[68:69], v[70:71], 0, v[74:75]
	global_load_dwordx4 v[226:229], v[68:69], off
	v_lshl_add_u64 v[68:69], v[72:73], 0, v[74:75]
	global_load_dwordx4 v[230:233], v[68:69], off
	v_ashrrev_i32_e32 v66, 3, v79
	v_ashrrev_i32_e32 v67, 31, v66
	v_lshlrev_b64 v[74:75], 9, v[66:67]
	v_lshl_add_u64 v[68:69], v[70:71], 0, v[74:75]
	global_load_dwordx4 v[234:237], v[68:69], off
	v_lshl_add_u64 v[68:69], v[72:73], 0, v[74:75]
	global_load_dwordx4 v[238:241], v[68:69], off
	v_ashrrev_i32_e32 v66, 3, v80
	v_ashrrev_i32_e32 v67, 31, v66
	v_lshlrev_b64 v[74:75], 9, v[66:67]
	v_lshl_add_u64 v[68:69], v[70:71], 0, v[74:75]
	global_load_dwordx4 v[242:245], v[68:69], off
	v_lshl_add_u64 v[68:69], v[72:73], 0, v[74:75]
	global_load_dwordx4 v[246:249], v[68:69], off
	v_ashrrev_i32_e32 v66, 3, v115
	v_mad_u32_u24 v66, v66, s90, v0
	s_waitcnt vmcnt(7)
	ds_write_b128 v66, v[218:221] offset:34816
	s_waitcnt vmcnt(6)
	ds_write_b128 v66, v[222:225] offset:53248
	v_ashrrev_i32_e32 v66, 3, v78
	v_mad_u32_u24 v66, v66, s90, v0
	s_waitcnt vmcnt(5)
	ds_write_b128 v66, v[226:229] offset:34816
	s_waitcnt vmcnt(4)
	ds_write_b128 v66, v[230:233] offset:53248
	v_ashrrev_i32_e32 v66, 3, v79
	v_mad_u32_u24 v66, v66, s90, v0
	s_waitcnt vmcnt(3)
	ds_write_b128 v66, v[234:237] offset:34816
	s_waitcnt vmcnt(2)
	ds_write_b128 v66, v[238:241] offset:53248
	v_ashrrev_i32_e32 v66, 3, v80
	v_mad_u32_u24 v66, v66, s90, v0
	s_waitcnt vmcnt(1)
	ds_write_b128 v66, v[242:245] offset:34816
	s_waitcnt vmcnt(0)
	ds_write_b128 v66, v[246:249] offset:53248
	v_cmp_gt_u32_e32 vcc, 64, v115
	s_nop 3
	s_and_saveexec_b64 s[34:35], vcc
	s_cbranch_execz .LBB0_295
	v_xor_b32_e32 v0, 63, v115
	v_cndmask_b32_e64 v68, v0, v82, s[42:43]
	s_or_b32 s6, s79, s80
	v_or_b32_e32 v0, s6, v68
	v_lshlrev_b64 v[66:67], 6, v[0:1]
	v_lshl_add_u64 v[66:67], s[10:11], 0, v[66:67]
	global_load_dword v0, v[66:67], off
	s_nop 0
	global_load_dword v66, v[66:67], off offset:16
	v_lshlrev_b32_e32 v68, 2, v68
	s_waitcnt vmcnt(0)
	v_max_f32_e32 v67, v66, v66
	v_mul_f32_e64 v66, |v66|, s76
	v_exp_f32_e32 v66, v66
	v_min_f32_e32 v67, 0, v67
	v_add_f32_e32 v66, 1.0, v66
	v_log_f32_e32 v66, v66
	s_nop 0
	v_fmac_f32_e32 v67, 0xbf317218, v66
	v_add_u32_e32 v66, -1, v183
	v_cmp_lt_i32_e32 vcc, v66, v184
	s_nop 1
	v_cndmask_b32_e32 v66, v66, v183, vcc
	v_lshlrev_b32_e32 v66, 2, v66
	ds_bpermute_b32 v69, v66, v67
	v_cmp_eq_u32_e32 vcc, 0, v82
	s_waitcnt lgkmcnt(0)
	v_add_f32_e32 v69, v67, v69
	v_cndmask_b32_e32 v67, v69, v67, vcc
	v_add_u32_e32 v69, -2, v183
	v_cmp_lt_i32_e64 s[6:7], v69, v184
	s_nop 1
	v_cndmask_b32_e64 v69, v69, v183, s[6:7]
	v_lshlrev_b32_e32 v69, 2, v69
	ds_bpermute_b32 v70, v69, v67
	v_cmp_gt_u32_e64 s[6:7], 2, v82
	s_waitcnt lgkmcnt(0)
	v_add_f32_e32 v70, v67, v70
	v_cndmask_b32_e64 v67, v70, v67, s[6:7]
	v_add_u32_e32 v70, -4, v183
	v_cmp_lt_i32_e64 s[8:9], v70, v184
	s_nop 1
	v_cndmask_b32_e64 v70, v70, v183, s[8:9]
	v_lshlrev_b32_e32 v70, 2, v70
	ds_bpermute_b32 v71, v70, v67
	v_cmp_gt_u32_e64 s[8:9], 4, v82
	s_waitcnt lgkmcnt(0)
	v_add_f32_e32 v71, v67, v71
	v_cndmask_b32_e64 v67, v71, v67, s[8:9]
	v_add_u32_e32 v71, -8, v183
	v_cmp_lt_i32_e64 s[44:45], v71, v184
	s_nop 1
	v_cndmask_b32_e64 v71, v71, v183, s[44:45]
	v_lshlrev_b32_e32 v71, 2, v71
	ds_bpermute_b32 v72, v71, v67
	v_cmp_gt_u32_e64 s[44:45], 8, v82
	s_waitcnt lgkmcnt(0)
	v_add_f32_e32 v72, v67, v72
	v_cndmask_b32_e64 v67, v72, v67, s[44:45]
	v_add_u32_e32 v72, -16, v183
	v_cmp_lt_i32_e64 s[46:47], v72, v184
	s_nop 1
	v_cndmask_b32_e64 v72, v72, v183, s[46:47]
	v_lshlrev_b32_e32 v72, 2, v72
	ds_bpermute_b32 v73, v72, v67
	v_cmp_gt_u32_e64 s[46:47], 16, v82
	s_waitcnt lgkmcnt(0)
	v_add_f32_e32 v73, v67, v73
	v_cndmask_b32_e64 v67, v73, v67, s[46:47]
	v_subrev_u32_e32 v73, 32, v183
	v_cmp_lt_i32_e64 s[48:49], v73, v184
	s_nop 1
	v_cndmask_b32_e64 v73, v73, v183, s[48:49]
	v_lshlrev_b32_e32 v73, 2, v73
	ds_bpermute_b32 v74, v73, v67
	v_cmp_gt_u32_e64 s[48:49], 32, v82
	s_waitcnt lgkmcnt(0)
	v_add_f32_e32 v74, v67, v74
	v_cndmask_b32_e64 v74, v74, v67, s[48:49]
	v_sub_f32_e32 v75, v0, v74
	ds_bpermute_b32 v0, v66, v75
	s_waitcnt lgkmcnt(0)
	v_max_f32_e32 v0, v0, v0
	v_max_f32_e32 v0, v75, v0
	v_cndmask_b32_e32 v0, v0, v75, vcc
	ds_bpermute_b32 v66, v69, v0
	v_add_u32_e32 v69, 0x11800, v68
	ds_write_b32 v69, v75
	s_waitcnt lgkmcnt(1)
	v_max_f32_e32 v66, v66, v66
	v_max_f32_e32 v66, v0, v66
	v_cndmask_b32_e64 v0, v66, v0, s[6:7]
	ds_bpermute_b32 v66, v70, v0
	v_add_u32_e32 v70, 0x11900, v68
	s_waitcnt lgkmcnt(0)
	v_max_f32_e32 v66, v66, v66
	v_max_f32_e32 v66, v0, v66
	v_cndmask_b32_e64 v0, v66, v0, s[8:9]
	ds_bpermute_b32 v66, v71, v0
	s_waitcnt lgkmcnt(0)
	v_max_f32_e32 v66, v66, v66
	v_max_f32_e32 v66, v0, v66
	v_cndmask_b32_e64 v0, v66, v0, s[44:45]
	ds_bpermute_b32 v66, v72, v0
	s_waitcnt lgkmcnt(0)
	v_max_f32_e32 v66, v66, v66
	v_max_f32_e32 v66, v0, v66
	v_cndmask_b32_e64 v0, v66, v0, s[46:47]
	ds_bpermute_b32 v66, v73, v0
	v_max_f32_e32 v67, v0, v0
	s_waitcnt lgkmcnt(0)
	v_max_f32_e32 v66, v66, v66
	v_max_f32_e32 v66, v67, v66
	v_cndmask_b32_e64 v0, v66, v0, s[48:49]
	v_max_f32_e32 v0, v0, v0
	v_max_f32_e32 v66, v117, v117
	v_max_f32_e32 v0, v66, v0
	v_add_f32_e32 v66, v74, v0
	v_sub_f32_e32 v69, v74, v66
	ds_write_b32 v70, v69
	v_add_f32_e32 v69, v117, v74
	v_sub_f32_e32 v69, v69, v66
	v_lshl_or_b32 v67, v183, 2, v192
	v_mul_f32_e32 v69, 0x3fb8aa3b, v69
	ds_bpermute_b32 v0, v67, v74
	ds_bpermute_b32 v67, v67, v66
	v_exp_f32_e32 v69, v69
	v_mul_f32_e32 v66, 0xbfb8aa3b, v66
	v_exp_f32_e32 v66, v66
	v_add_u32_e32 v70, 0x11a00, v68
	ds_write_b32 v70, v69
	v_add_u32_e32 v69, 0x11b00, v68
	ds_write_b32 v69, v66
	s_waitcnt lgkmcnt(3)
	v_add_f32_e32 v66, v75, v0
	s_waitcnt lgkmcnt(2)
	v_sub_f32_e32 v66, v66, v67
	v_mul_f32_e32 v66, 0x3fb8aa3b, v66
	v_exp_f32_e32 v66, v66
	v_add_u32_e32 v68, 0x11c00, v68
	ds_write_b32 v68, v66
	s_and_b64 exec, exec, vcc
	s_cbranch_execz .LBB0_295
	v_add_f32_e32 v0, v117, v0
	v_sub_f32_e32 v0, v0, v67
	v_mul_f32_e32 v0, 0x3fb8aa3b, v0
	v_exp_f32_e32 v66, v0
	ds_write_b64 v180, v[66:67]

.Lg357_loop:
	v_add_u32_e32 v136, s13, v134
	v_add_u32_e32 v137, s13, v135
	s_add_i32 s7, s7, 1
	s_add_u32 s73, s13, 0x6000
	s_cmp_lt_u32 s73, 0x12000
	s_cselect_b32 s73, s73, 0
	v_add_u32_e32 v138, s73, v132
	v_add_u32_e32 v139, s73, v133
	s_waitcnt lgkmcnt(0)
	v_mfma_f32_32x32x16_bf16 v[114:129], v[162:165], v[228:231], v[114:129]
	ds_read_b128 v[166:169], v136 offset:0
	ds_read_b128 v[232:235], v137 offset:0
	s_add_i32 s14, s7, 2
	s_lshl_b64 s[10:11], s[14:15], 14
	v_lshl_add_u64 v[244:245], v[154:155], 0, s[10:11]
	v_mfma_f32_32x32x16_bf16 v[98:113], v[162:165], v[236:239], v[98:113]
	ds_read_b128 v[240:243], v137 offset:2048
	ds_read_b128 v[208:211], v136 offset:2048
	s_add_u32 s10, s10, 0x1000
	s_addc_u32 s11, s11, 0
	v_lshl_add_u64 v[246:247], v[154:155], 0, s[10:11]
	v_mfma_f32_32x32x16_bf16 v[82:97], v[204:207], v[228:231], v[82:97]
	ds_read_b128 v[216:219], v136 offset:4096
	ds_read_b128 v[224:227], v136 offset:6144
	s_add_u32 s10, s10, 0x1000
	s_addc_u32 s11, s11, 0
	v_lshl_add_u64 v[248:249], v[154:155], 0, s[10:11]
	v_mfma_f32_32x32x16_bf16 v[66:81], v[204:207], v[236:239], v[66:81]
	s_add_u32 s10, s10, 0x1000
	s_addc_u32 s11, s11, 0
	v_lshl_add_u64 v[140:141], v[154:155], 0, s[10:11]
	v_mfma_f32_32x32x16_bf16 v[50:65], v[212:215], v[228:231], v[50:65]
	s_lshl_b64 s[10:11], s[14:15], 13
	v_lshl_add_u64 v[142:143], v[156:157], 0, s[10:11]
	v_mfma_f32_32x32x16_bf16 v[34:49], v[212:215], v[236:239], v[34:49]
	s_add_u32 s10, s10, 0x1000
	s_addc_u32 s11, s11, 0
	v_lshl_add_u64 v[144:145], v[156:157], 0, s[10:11]
	v_mfma_f32_32x32x16_bf16 v[18:33], v[220:223], v[228:231], v[18:33]
	v_mfma_f32_32x32x16_bf16 v[2:17], v[220:223], v[236:239], v[2:17]
	s_waitcnt vmcnt(6) lgkmcnt(0)
	s_barrier
	s_add_u32 m0, s13, s72
	v_mfma_f32_32x32x16_bf16 v[114:129], v[166:169], v[232:235], v[114:129]
	global_load_lds_dwordx4 v[244:245], off
	ds_read_b128 v[162:165], v138 offset:0
	ds_read_b128 v[228:231], v139 offset:0
	s_add_u32 m0, m0, 0x1000
	v_mfma_f32_32x32x16_bf16 v[98:113], v[166:169], v[240:243], v[98:113]
	global_load_lds_dwordx4 v[246:247], off
	ds_read_b128 v[236:239], v139 offset:2048
	ds_read_b128 v[204:207], v138 offset:2048
	s_add_u32 m0, m0, 0x1000
	v_mfma_f32_32x32x16_bf16 v[82:97], v[208:211], v[232:235], v[82:97]
	global_load_lds_dwordx4 v[248:249], off
	ds_read_b128 v[212:215], v138 offset:4096
	ds_read_b128 v[220:223], v138 offset:6144
	s_add_u32 m0, m0, 0x1000
	v_mfma_f32_32x32x16_bf16 v[66:81], v[208:211], v[240:243], v[66:81]
	global_load_lds_dwordx4 v[140:141], off
	s_add_u32 m0, m0, 0x1000
	v_mfma_f32_32x32x16_bf16 v[50:65], v[216:219], v[232:235], v[50:65]
	global_load_lds_dwordx4 v[142:143], off
	s_add_u32 m0, m0, 0x1000
	v_mfma_f32_32x32x16_bf16 v[34:49], v[216:219], v[240:243], v[34:49]
	global_load_lds_dwordx4 v[144:145], off
	v_mfma_f32_32x32x16_bf16 v[18:33], v[224:227], v[232:235], v[18:33]
	v_mfma_f32_32x32x16_bf16 v[2:17], v[224:227], v[240:243], v[2:17]
	s_mov_b32 s13, s73
	s_cmp_lg_u32 s7, 29
	s_cbranch_scc1 .Lg357_loop
	v_add_u32_e32 v136, s13, v134
	v_add_u32_e32 v137, s13, v135
	s_add_i32 s7, s7, 1
	s_add_u32 s73, s13, 0x6000
	s_cmp_lt_u32 s73, 0x12000
	s_cselect_b32 s73, s73, 0
	v_add_u32_e32 v138, s73, v132
	v_add_u32_e32 v139, s73, v133
	s_waitcnt lgkmcnt(0)
	v_mfma_f32_32x32x16_bf16 v[114:129], v[162:165], v[228:231], v[114:129]
	ds_read_b128 v[166:169], v136 offset:0
	ds_read_b128 v[232:235], v137 offset:0
	v_mfma_f32_32x32x16_bf16 v[98:113], v[162:165], v[236:239], v[98:113]
	ds_read_b128 v[240:243], v137 offset:2048
	ds_read_b128 v[208:211], v136 offset:2048
	v_mfma_f32_32x32x16_bf16 v[82:97], v[204:207], v[228:231], v[82:97]
	ds_read_b128 v[216:219], v136 offset:4096
	ds_read_b128 v[224:227], v136 offset:6144
	v_mfma_f32_32x32x16_bf16 v[66:81], v[204:207], v[236:239], v[66:81]
	v_mfma_f32_32x32x16_bf16 v[50:65], v[212:215], v[228:231], v[50:65]
	v_mfma_f32_32x32x16_bf16 v[34:49], v[212:215], v[236:239], v[34:49]
	v_mfma_f32_32x32x16_bf16 v[18:33], v[220:223], v[228:231], v[18:33]
	v_mfma_f32_32x32x16_bf16 v[2:17], v[220:223], v[236:239], v[2:17]
	s_waitcnt vmcnt(6) lgkmcnt(0)
	s_barrier
	v_mfma_f32_32x32x16_bf16 v[114:129], v[166:169], v[232:235], v[114:129]
	ds_read_b128 v[162:165], v138 offset:0
	ds_read_b128 v[228:231], v139 offset:0
	v_mfma_f32_32x32x16_bf16 v[98:113], v[166:169], v[240:243], v[98:113]
	ds_read_b128 v[236:239], v139 offset:2048
	ds_read_b128 v[204:207], v138 offset:2048
	v_mfma_f32_32x32x16_bf16 v[82:97], v[208:211], v[232:235], v[82:97]
	ds_read_b128 v[212:215], v138 offset:4096
	ds_read_b128 v[220:223], v138 offset:6144
	v_mfma_f32_32x32x16_bf16 v[66:81], v[208:211], v[240:243], v[66:81]
	v_mfma_f32_32x32x16_bf16 v[50:65], v[216:219], v[232:235], v[50:65]
	v_mfma_f32_32x32x16_bf16 v[34:49], v[216:219], v[240:243], v[34:49]
	v_mfma_f32_32x32x16_bf16 v[18:33], v[224:227], v[232:235], v[18:33]
	v_mfma_f32_32x32x16_bf16 v[2:17], v[224:227], v[240:243], v[2:17]
	s_mov_b32 s13, s73
	v_add_u32_e32 v136, s13, v134
	v_add_u32_e32 v137, s13, v135
	s_add_i32 s7, s7, 1
	s_add_u32 s73, s13, 0x6000
	s_cmp_lt_u32 s73, 0x12000
	s_cselect_b32 s73, s73, 0
	v_add_u32_e32 v138, s73, v132
	v_add_u32_e32 v139, s73, v133
	s_waitcnt lgkmcnt(0)
	v_mfma_f32_32x32x16_bf16 v[114:129], v[162:165], v[228:231], v[114:129]
	ds_read_b128 v[166:169], v136 offset:0
	ds_read_b128 v[232:235], v137 offset:0
	v_mfma_f32_32x32x16_bf16 v[98:113], v[162:165], v[236:239], v[98:113]
	ds_read_b128 v[240:243], v137 offset:2048
	ds_read_b128 v[208:211], v136 offset:2048
	v_mfma_f32_32x32x16_bf16 v[82:97], v[204:207], v[228:231], v[82:97]
	ds_read_b128 v[216:219], v136 offset:4096
	ds_read_b128 v[224:227], v136 offset:6144
	v_mfma_f32_32x32x16_bf16 v[66:81], v[204:207], v[236:239], v[66:81]
	v_mfma_f32_32x32x16_bf16 v[50:65], v[212:215], v[228:231], v[50:65]
	v_mfma_f32_32x32x16_bf16 v[34:49], v[212:215], v[236:239], v[34:49]
	v_mfma_f32_32x32x16_bf16 v[18:33], v[220:223], v[228:231], v[18:33]
	v_mfma_f32_32x32x16_bf16 v[2:17], v[220:223], v[236:239], v[2:17]
	s_waitcnt vmcnt(0) lgkmcnt(0)
	s_barrier
	v_mfma_f32_32x32x16_bf16 v[114:129], v[166:169], v[232:235], v[114:129]
	ds_read_b128 v[162:165], v138 offset:0
	ds_read_b128 v[228:231], v139 offset:0
	v_mfma_f32_32x32x16_bf16 v[98:113], v[166:169], v[240:243], v[98:113]
	ds_read_b128 v[236:239], v139 offset:2048
	ds_read_b128 v[204:207], v138 offset:2048
	v_mfma_f32_32x32x16_bf16 v[82:97], v[208:211], v[232:235], v[82:97]
	ds_read_b128 v[212:215], v138 offset:4096
	ds_read_b128 v[220:223], v138 offset:6144
	v_mfma_f32_32x32x16_bf16 v[66:81], v[208:211], v[240:243], v[66:81]
	v_mfma_f32_32x32x16_bf16 v[50:65], v[216:219], v[232:235], v[50:65]
	v_mfma_f32_32x32x16_bf16 v[34:49], v[216:219], v[240:243], v[34:49]
	v_mfma_f32_32x32x16_bf16 v[18:33], v[224:227], v[232:235], v[18:33]
	v_mfma_f32_32x32x16_bf16 v[2:17], v[224:227], v[240:243], v[2:17]
	s_mov_b32 s13, s73
	v_add_u32_e32 v136, s13, v134
	v_add_u32_e32 v137, s13, v135
	s_add_i32 s7, s7, 1
	s_waitcnt lgkmcnt(0)
	v_mfma_f32_32x32x16_bf16 v[114:129], v[162:165], v[228:231], v[114:129]
	ds_read_b128 v[166:169], v136 offset:0
	ds_read_b128 v[232:235], v137 offset:0
	v_mfma_f32_32x32x16_bf16 v[98:113], v[162:165], v[236:239], v[98:113]
	ds_read_b128 v[240:243], v137 offset:2048
	ds_read_b128 v[208:211], v136 offset:2048
	v_mfma_f32_32x32x16_bf16 v[82:97], v[204:207], v[228:231], v[82:97]
	ds_read_b128 v[216:219], v136 offset:4096
	ds_read_b128 v[224:227], v136 offset:6144
	v_mfma_f32_32x32x16_bf16 v[66:81], v[204:207], v[236:239], v[66:81]
	v_mfma_f32_32x32x16_bf16 v[50:65], v[212:215], v[228:231], v[50:65]
	v_mfma_f32_32x32x16_bf16 v[34:49], v[212:215], v[236:239], v[34:49]
	v_mfma_f32_32x32x16_bf16 v[18:33], v[220:223], v[228:231], v[18:33]
	v_mfma_f32_32x32x16_bf16 v[2:17], v[220:223], v[236:239], v[2:17]
	s_waitcnt lgkmcnt(0)
	v_mfma_f32_32x32x16_bf16 v[114:129], v[166:169], v[232:235], v[114:129]
	v_mfma_f32_32x32x16_bf16 v[98:113], v[166:169], v[240:243], v[98:113]
	v_mfma_f32_32x32x16_bf16 v[82:97], v[208:211], v[232:235], v[82:97]
	v_mfma_f32_32x32x16_bf16 v[66:81], v[208:211], v[240:243], v[66:81]
	v_mfma_f32_32x32x16_bf16 v[50:65], v[216:219], v[232:235], v[50:65]
	v_mfma_f32_32x32x16_bf16 v[34:49], v[216:219], v[240:243], v[34:49]
	v_mfma_f32_32x32x16_bf16 v[18:33], v[224:227], v[232:235], v[18:33]
	v_mfma_f32_32x32x16_bf16 v[2:17], v[224:227], v[240:243], v[2:17]
	s_mov_b32 s14, 31
	s_lshl_b64 s[10:11], s[14:15], 13
	s_movk_i32 s13, 0x7800
	s_movk_i32 s72, 0x6000
	s_mov_b32 s73, 0xc000
	v_mov_b32_e32 v0, v171
	s_barrier
	s_waitcnt vmcnt(4)
	v_lshrrev_b32_e32 v130, 1, v0
	v_and_b32_e32 v130, 0xfffffc0, v130
	v_lshrrev_b32_e32 v131, 3, v0
	v_and_or_b32 v130, v131, 4, v130
	v_and_b32_e32 v0, 0x5f, v0
	v_mul_lo_u32 v130, v130, s53
	v_lshl_add_u32 v0, v0, 2, v130
	s_barrier
	ds_write2_b32 v0, v114, v98 offset1:32
	ds_write2_b32 v0, v115, v99 offset0:132 offset1:164
	v_add_u32_e32 v98, 0x400, v0
	ds_write2_b32 v98, v116, v100 offset0:8 offset1:40
	ds_write2_b32 v98, v117, v101 offset0:140 offset1:172
	v_add_u32_e32 v98, 0x1000, v0
	ds_write2_b32 v98, v118, v102 offset0:32 offset1:64
	ds_write2_b32 v98, v119, v103 offset0:164 offset1:196
	v_add_u32_e32 v98, 0x1400, v0
	ds_write2_b32 v98, v120, v104 offset0:40 offset1:72
	ds_write2_b32 v98, v121, v105 offset0:172 offset1:204
	v_add_u32_e32 v98, 0x2000, v0
	ds_write2_b32 v98, v122, v106 offset0:64 offset1:96
	ds_write2_b32 v98, v123, v107 offset0:196 offset1:228
	v_add_u32_e32 v98, 0x2400, v0
	ds_write2_b32 v98, v124, v108 offset0:72 offset1:104
	ds_write2_b32 v98, v125, v109 offset0:204 offset1:236
	v_add_u32_e32 v98, 0x3000, v0
	ds_write2_b32 v98, v126, v110 offset0:96 offset1:128
	v_add_u32_e32 v98, 0x3200, v0
	ds_write2_b32 v98, v127, v111 offset0:100 offset1:132
	v_add_u32_e32 v98, 0x3400, v0
	ds_write2_b32 v98, v128, v112 offset0:104 offset1:136
	v_add_u32_e32 v98, 0x3600, v0
	ds_write2_b32 v98, v129, v113 offset0:108 offset1:140
	v_add_u32_e32 v98, 0x4000, v0
	ds_write2_b32 v98, v82, v66 offset0:128 offset1:160
	v_add_u32_e32 v66, 0x4400, v0
	ds_write2_b32 v66, v83, v67 offset0:4 offset1:36
	ds_write2_b32 v66, v84, v68 offset0:136 offset1:168
	v_add_u32_e32 v66, 0x4800, v0
	ds_write2_b32 v66, v85, v69 offset0:12 offset1:44
	v_add_u32_e32 v66, 0x5000, v0
	s_lshl_b32 s13, s9, 8
	ds_write2_b32 v66, v86, v70 offset0:160 offset1:192
	v_add_u32_e32 v66, 0x5400, v0
	s_lshl_b32 s34, s6, 7
	ds_write2_b32 v66, v87, v71 offset0:36 offset1:68
	ds_write2_b32 v66, v88, v72 offset0:168 offset1:200
	v_add_u32_e32 v66, 0x5800, v0
	s_add_i32 s6, s13, 0xffffe000
	ds_write2_b32 v66, v89, v73 offset0:44 offset1:76
	v_add_u32_e32 v66, 0x6000, v0
	s_lshr_b32 s6, s6, 12
	ds_write2_b32 v66, v90, v74 offset0:192 offset1:224
	v_add_u32_e32 v66, 0x6400, v0
	s_mulk_i32 s6, 0x1800
	ds_write2_b32 v66, v91, v75 offset0:68 offset1:100
	ds_write2_b32 v66, v92, v76 offset0:200 offset1:232
	v_add_u32_e32 v66, 0x6800, v0
	s_addk_i32 s6, 0x1800
	ds_write2_b32 v66, v93, v77 offset0:76 offset1:108
	v_add_u32_e32 v66, 0x7200, v0
	s_cmp_gt_u32 s8, 31
	ds_write2_b32 v66, v94, v78 offset0:96 offset1:128
	v_add_u32_e32 v66, 0x7400, v0
	s_cselect_b32 s14, s6, 0
	ds_write2_b32 v66, v95, v79 offset0:100 offset1:132
	v_add_u32_e32 v66, 0x7600, v0
	v_add_u32_e32 v0, 0x7800, v0
	v_mov_b32_e32 v76, v171
	s_lshl_b64 s[6:7], s[14:15], 2
	ds_write2_b32 v66, v96, v80 offset0:104 offset1:136
	ds_write2_b32 v0, v97, v81 offset0:108 offset1:140
	s_waitcnt lgkmcnt(0)
	s_barrier
	s_add_u32 s6, s61, s6
	v_lshlrev_b32_e32 v0, 3, v76
	v_and_b32_e32 v0, 0x78, v0
	s_addc_u32 s7, s79, s7
	v_or_b32_e32 v0, s34, v0
	s_add_u32 s8, s6, 0x1d642000
	s_addc_u32 s9, s7, 0
	v_lshlrev_b64 v[74:75], 2, v[0:1]
	v_lshl_add_u64 v[70:71], s[8:9], 0, v[74:75]
	global_load_dwordx4 v[66:69], v[70:71], off offset:16
	s_nop 0
	global_load_dwordx4 v[70:73], v[70:71], off
	v_ashrrev_i32_e32 v90, 4, v76
	v_lshl_add_u64 v[82:83], s[56:57], 0, v[74:75]
	v_mul_lo_u32 v74, v90, s53
	v_and_b32_e32 v75, 15, v76
	s_mov_b32 s14, 0
	v_lshl_add_u32 v91, v75, 5, v74
	v_lshlrev_b32_e32 v92, 1, v90
	s_branch .LBB0_360

.Lg432_loop:
	v_add_u32_e32 v136, s7, v134
	v_add_u32_e32 v137, s7, v135
	s_add_i32 s6, s6, 1
	s_add_u32 s73, s7, 0x6000
	s_cmp_lt_u32 s73, 0x12000
	s_cselect_b32 s73, s73, 0
	v_add_u32_e32 v138, s73, v132
	v_add_u32_e32 v139, s73, v133
	s_waitcnt lgkmcnt(0)
	v_mfma_f32_32x32x16_bf16 v[114:129], v[162:165], v[228:231], v[114:129]
	ds_read_b128 v[166:169], v136 offset:0
	ds_read_b128 v[232:235], v137 offset:0
	s_add_i32 s14, s6, 2
	s_lshl_b64 s[12:13], s[14:15], 14
	v_lshl_add_u64 v[244:245], v[154:155], 0, s[12:13]
	v_mfma_f32_32x32x16_bf16 v[98:113], v[162:165], v[236:239], v[98:113]
	ds_read_b128 v[240:243], v137 offset:2048
	ds_read_b128 v[208:211], v136 offset:2048
	s_add_u32 s12, s12, 0x1000
	s_addc_u32 s13, s13, 0
	v_lshl_add_u64 v[246:247], v[154:155], 0, s[12:13]
	v_mfma_f32_32x32x16_bf16 v[82:97], v[204:207], v[228:231], v[82:97]
	ds_read_b128 v[216:219], v136 offset:4096
	ds_read_b128 v[224:227], v136 offset:6144
	s_add_u32 s12, s12, 0x1000
	s_addc_u32 s13, s13, 0
	v_lshl_add_u64 v[248:249], v[154:155], 0, s[12:13]
	v_mfma_f32_32x32x16_bf16 v[66:81], v[204:207], v[236:239], v[66:81]
	s_add_u32 s12, s12, 0x1000
	s_addc_u32 s13, s13, 0
	v_lshl_add_u64 v[140:141], v[154:155], 0, s[12:13]
	v_mfma_f32_32x32x16_bf16 v[50:65], v[212:215], v[228:231], v[50:65]
	s_lshl_b64 s[12:13], s[14:15], 13
	v_lshl_add_u64 v[142:143], v[156:157], 0, s[12:13]
	v_mfma_f32_32x32x16_bf16 v[34:49], v[212:215], v[236:239], v[34:49]
	s_add_u32 s12, s12, 0x1000
	s_addc_u32 s13, s13, 0
	v_lshl_add_u64 v[144:145], v[156:157], 0, s[12:13]
	v_mfma_f32_32x32x16_bf16 v[18:33], v[220:223], v[228:231], v[18:33]
	v_mfma_f32_32x32x16_bf16 v[2:17], v[220:223], v[236:239], v[2:17]
	s_waitcnt vmcnt(6) lgkmcnt(0)
	s_barrier
	s_add_u32 m0, s7, s72
	v_mfma_f32_32x32x16_bf16 v[114:129], v[166:169], v[232:235], v[114:129]
	global_load_lds_dwordx4 v[244:245], off
	ds_read_b128 v[162:165], v138 offset:0
	ds_read_b128 v[228:231], v139 offset:0
	s_add_u32 m0, m0, 0x1000
	v_mfma_f32_32x32x16_bf16 v[98:113], v[166:169], v[240:243], v[98:113]
	global_load_lds_dwordx4 v[246:247], off
	ds_read_b128 v[236:239], v139 offset:2048
	ds_read_b128 v[204:207], v138 offset:2048
	s_add_u32 m0, m0, 0x1000
	v_mfma_f32_32x32x16_bf16 v[82:97], v[208:211], v[232:235], v[82:97]
	global_load_lds_dwordx4 v[248:249], off
	ds_read_b128 v[212:215], v138 offset:4096
	ds_read_b128 v[220:223], v138 offset:6144
	s_add_u32 m0, m0, 0x1000
	v_mfma_f32_32x32x16_bf16 v[66:81], v[208:211], v[240:243], v[66:81]
	global_load_lds_dwordx4 v[140:141], off
	s_add_u32 m0, m0, 0x1000
	v_mfma_f32_32x32x16_bf16 v[50:65], v[216:219], v[232:235], v[50:65]
	global_load_lds_dwordx4 v[142:143], off
	s_add_u32 m0, m0, 0x1000
	v_mfma_f32_32x32x16_bf16 v[34:49], v[216:219], v[240:243], v[34:49]
	global_load_lds_dwordx4 v[144:145], off
	v_mfma_f32_32x32x16_bf16 v[18:33], v[224:227], v[232:235], v[18:33]
	v_mfma_f32_32x32x16_bf16 v[2:17], v[224:227], v[240:243], v[2:17]
	s_mov_b32 s7, s73
	s_cmp_lg_u32 s6, 29
	s_cbranch_scc1 .Lg432_loop
	v_add_u32_e32 v136, s7, v134
	v_add_u32_e32 v137, s7, v135
	s_add_i32 s6, s6, 1
	s_add_u32 s73, s7, 0x6000
	s_cmp_lt_u32 s73, 0x12000
	s_cselect_b32 s73, s73, 0
	v_add_u32_e32 v138, s73, v132
	v_add_u32_e32 v139, s73, v133
	s_waitcnt lgkmcnt(0)
	v_mfma_f32_32x32x16_bf16 v[114:129], v[162:165], v[228:231], v[114:129]
	ds_read_b128 v[166:169], v136 offset:0
	ds_read_b128 v[232:235], v137 offset:0
	v_mfma_f32_32x32x16_bf16 v[98:113], v[162:165], v[236:239], v[98:113]
	ds_read_b128 v[240:243], v137 offset:2048
	ds_read_b128 v[208:211], v136 offset:2048
	v_mfma_f32_32x32x16_bf16 v[82:97], v[204:207], v[228:231], v[82:97]
	ds_read_b128 v[216:219], v136 offset:4096
	ds_read_b128 v[224:227], v136 offset:6144
	v_mfma_f32_32x32x16_bf16 v[66:81], v[204:207], v[236:239], v[66:81]
	v_mfma_f32_32x32x16_bf16 v[50:65], v[212:215], v[228:231], v[50:65]
	v_mfma_f32_32x32x16_bf16 v[34:49], v[212:215], v[236:239], v[34:49]
	v_mfma_f32_32x32x16_bf16 v[18:33], v[220:223], v[228:231], v[18:33]
	v_mfma_f32_32x32x16_bf16 v[2:17], v[220:223], v[236:239], v[2:17]
	s_waitcnt vmcnt(6) lgkmcnt(0)
	s_barrier
	v_mfma_f32_32x32x16_bf16 v[114:129], v[166:169], v[232:235], v[114:129]
	ds_read_b128 v[162:165], v138 offset:0
	ds_read_b128 v[228:231], v139 offset:0
	v_mfma_f32_32x32x16_bf16 v[98:113], v[166:169], v[240:243], v[98:113]
	ds_read_b128 v[236:239], v139 offset:2048
	ds_read_b128 v[204:207], v138 offset:2048
	v_mfma_f32_32x32x16_bf16 v[82:97], v[208:211], v[232:235], v[82:97]
	ds_read_b128 v[212:215], v138 offset:4096
	ds_read_b128 v[220:223], v138 offset:6144
	v_mfma_f32_32x32x16_bf16 v[66:81], v[208:211], v[240:243], v[66:81]
	v_mfma_f32_32x32x16_bf16 v[50:65], v[216:219], v[232:235], v[50:65]
	v_mfma_f32_32x32x16_bf16 v[34:49], v[216:219], v[240:243], v[34:49]
	v_mfma_f32_32x32x16_bf16 v[18:33], v[224:227], v[232:235], v[18:33]
	v_mfma_f32_32x32x16_bf16 v[2:17], v[224:227], v[240:243], v[2:17]
	s_mov_b32 s7, s73
	v_add_u32_e32 v136, s7, v134
	v_add_u32_e32 v137, s7, v135
	s_add_i32 s6, s6, 1
	s_add_u32 s73, s7, 0x6000
	s_cmp_lt_u32 s73, 0x12000
	s_cselect_b32 s73, s73, 0
	v_add_u32_e32 v138, s73, v132
	v_add_u32_e32 v139, s73, v133
	s_waitcnt lgkmcnt(0)
	v_mfma_f32_32x32x16_bf16 v[114:129], v[162:165], v[228:231], v[114:129]
	ds_read_b128 v[166:169], v136 offset:0
	ds_read_b128 v[232:235], v137 offset:0
	v_mfma_f32_32x32x16_bf16 v[98:113], v[162:165], v[236:239], v[98:113]
	ds_read_b128 v[240:243], v137 offset:2048
	ds_read_b128 v[208:211], v136 offset:2048
	v_mfma_f32_32x32x16_bf16 v[82:97], v[204:207], v[228:231], v[82:97]
	ds_read_b128 v[216:219], v136 offset:4096
	ds_read_b128 v[224:227], v136 offset:6144
	v_mfma_f32_32x32x16_bf16 v[66:81], v[204:207], v[236:239], v[66:81]
	v_mfma_f32_32x32x16_bf16 v[50:65], v[212:215], v[228:231], v[50:65]
	v_mfma_f32_32x32x16_bf16 v[34:49], v[212:215], v[236:239], v[34:49]
	v_mfma_f32_32x32x16_bf16 v[18:33], v[220:223], v[228:231], v[18:33]
	v_mfma_f32_32x32x16_bf16 v[2:17], v[220:223], v[236:239], v[2:17]
	s_waitcnt vmcnt(0) lgkmcnt(0)
	s_barrier
	v_mfma_f32_32x32x16_bf16 v[114:129], v[166:169], v[232:235], v[114:129]
	ds_read_b128 v[162:165], v138 offset:0
	ds_read_b128 v[228:231], v139 offset:0
	v_mfma_f32_32x32x16_bf16 v[98:113], v[166:169], v[240:243], v[98:113]
	ds_read_b128 v[236:239], v139 offset:2048
	ds_read_b128 v[204:207], v138 offset:2048
	v_mfma_f32_32x32x16_bf16 v[82:97], v[208:211], v[232:235], v[82:97]
	ds_read_b128 v[212:215], v138 offset:4096
	ds_read_b128 v[220:223], v138 offset:6144
	v_mfma_f32_32x32x16_bf16 v[66:81], v[208:211], v[240:243], v[66:81]
	v_mfma_f32_32x32x16_bf16 v[50:65], v[216:219], v[232:235], v[50:65]
	v_mfma_f32_32x32x16_bf16 v[34:49], v[216:219], v[240:243], v[34:49]
	v_mfma_f32_32x32x16_bf16 v[18:33], v[224:227], v[232:235], v[18:33]
	v_mfma_f32_32x32x16_bf16 v[2:17], v[224:227], v[240:243], v[2:17]
	s_mov_b32 s7, s73
	v_add_u32_e32 v136, s7, v134
	v_add_u32_e32 v137, s7, v135
	s_add_i32 s6, s6, 1
	s_waitcnt lgkmcnt(0)
	v_mfma_f32_32x32x16_bf16 v[114:129], v[162:165], v[228:231], v[114:129]
	ds_read_b128 v[166:169], v136 offset:0
	ds_read_b128 v[232:235], v137 offset:0
	v_mfma_f32_32x32x16_bf16 v[98:113], v[162:165], v[236:239], v[98:113]
	ds_read_b128 v[240:243], v137 offset:2048
	ds_read_b128 v[208:211], v136 offset:2048
	v_mfma_f32_32x32x16_bf16 v[82:97], v[204:207], v[228:231], v[82:97]
	ds_read_b128 v[216:219], v136 offset:4096
	ds_read_b128 v[224:227], v136 offset:6144
	v_mfma_f32_32x32x16_bf16 v[66:81], v[204:207], v[236:239], v[66:81]
	v_mfma_f32_32x32x16_bf16 v[50:65], v[212:215], v[228:231], v[50:65]
	v_mfma_f32_32x32x16_bf16 v[34:49], v[212:215], v[236:239], v[34:49]
	v_mfma_f32_32x32x16_bf16 v[18:33], v[220:223], v[228:231], v[18:33]
	v_mfma_f32_32x32x16_bf16 v[2:17], v[220:223], v[236:239], v[2:17]
	s_waitcnt lgkmcnt(0)
	v_mfma_f32_32x32x16_bf16 v[114:129], v[166:169], v[232:235], v[114:129]
	v_mfma_f32_32x32x16_bf16 v[98:113], v[166:169], v[240:243], v[98:113]
	v_mfma_f32_32x32x16_bf16 v[82:97], v[208:211], v[232:235], v[82:97]
	v_mfma_f32_32x32x16_bf16 v[66:81], v[208:211], v[240:243], v[66:81]
	v_mfma_f32_32x32x16_bf16 v[50:65], v[216:219], v[232:235], v[50:65]
	v_mfma_f32_32x32x16_bf16 v[34:49], v[216:219], v[240:243], v[34:49]
	v_mfma_f32_32x32x16_bf16 v[18:33], v[224:227], v[232:235], v[18:33]
	v_mfma_f32_32x32x16_bf16 v[2:17], v[224:227], v[240:243], v[2:17]
	s_mov_b32 s14, 31
	s_lshl_b64 s[12:13], s[14:15], 13
	s_movk_i32 s7, 0x7800
	s_movk_i32 s72, 0x6000
	s_mov_b32 s73, 0xc000
	v_mov_b32_e32 v0, v171
	s_barrier
	s_movk_i32 s0, 0x210
	s_waitcnt vmcnt(4)
	v_lshrrev_b32_e32 v130, 1, v0
	v_and_b32_e32 v130, 0xfffffc0, v130
	v_lshrrev_b32_e32 v131, 3, v0
	v_and_or_b32 v130, v131, 4, v130
	v_and_b32_e32 v0, 0x5f, v0
	v_mul_lo_u32 v130, v130, s0
	v_lshl_add_u32 v0, v0, 2, v130
	s_barrier
	ds_write2_b32 v0, v114, v98 offset1:32
	ds_write2_b32 v0, v115, v99 offset0:132 offset1:164
	v_add_u32_e32 v98, 0x400, v0
	ds_write2_b32 v98, v116, v100 offset0:8 offset1:40
	ds_write2_b32 v98, v117, v101 offset0:140 offset1:172
	v_add_u32_e32 v98, 0x1000, v0
	ds_write2_b32 v98, v118, v102 offset0:32 offset1:64
	ds_write2_b32 v98, v119, v103 offset0:164 offset1:196
	v_add_u32_e32 v98, 0x1400, v0
	ds_write2_b32 v98, v120, v104 offset0:40 offset1:72
	ds_write2_b32 v98, v121, v105 offset0:172 offset1:204
	v_add_u32_e32 v98, 0x2000, v0
	ds_write2_b32 v98, v122, v106 offset0:64 offset1:96
	ds_write2_b32 v98, v123, v107 offset0:196 offset1:228
	v_add_u32_e32 v98, 0x2400, v0
	ds_write2_b32 v98, v124, v108 offset0:72 offset1:104
	ds_write2_b32 v98, v125, v109 offset0:204 offset1:236
	v_add_u32_e32 v98, 0x3000, v0
	ds_write2_b32 v98, v126, v110 offset0:96 offset1:128
	v_add_u32_e32 v98, 0x3200, v0
	ds_write2_b32 v98, v127, v111 offset0:100 offset1:132
	v_add_u32_e32 v98, 0x3400, v0
	ds_write2_b32 v98, v128, v112 offset0:104 offset1:136
	v_add_u32_e32 v98, 0x3600, v0
	ds_write2_b32 v98, v129, v113 offset0:108 offset1:140
	v_add_u32_e32 v98, 0x4000, v0
	ds_write2_b32 v98, v82, v66 offset0:128 offset1:160
	v_add_u32_e32 v66, 0x4400, v0
	ds_write2_b32 v66, v83, v67 offset0:4 offset1:36
	ds_write2_b32 v66, v84, v68 offset0:136 offset1:168
	v_add_u32_e32 v66, 0x4800, v0
	ds_write2_b32 v66, v85, v69 offset0:12 offset1:44
	v_add_u32_e32 v66, 0x5000, v0
	ds_write2_b32 v66, v86, v70 offset0:160 offset1:192
	v_add_u32_e32 v66, 0x5400, v0
	ds_write2_b32 v66, v87, v71 offset0:36 offset1:68
	ds_write2_b32 v66, v88, v72 offset0:168 offset1:200
	v_add_u32_e32 v66, 0x5800, v0
	ds_write2_b32 v66, v89, v73 offset0:44 offset1:76
	v_add_u32_e32 v66, 0x6000, v0
	ds_write2_b32 v66, v90, v74 offset0:192 offset1:224
	v_add_u32_e32 v66, 0x6400, v0
	ds_write2_b32 v66, v91, v75 offset0:68 offset1:100
	ds_write2_b32 v66, v92, v76 offset0:200 offset1:232
	v_add_u32_e32 v66, 0x6800, v0
	ds_write2_b32 v66, v93, v77 offset0:76 offset1:108
	v_add_u32_e32 v66, 0x7200, v0
	ds_write2_b32 v66, v94, v78 offset0:96 offset1:128
	v_add_u32_e32 v66, 0x7400, v0
	s_lshr_b32 s14, s42, 2
	ds_write2_b32 v66, v95, v79 offset0:100 offset1:132
	v_add_u32_e32 v66, 0x7600, v0
	v_add_u32_e32 v0, 0x7800, v0
	v_mov_b32_e32 v105, v171
	s_cmp_lt_i32 s14, 14
	s_mov_b64 s[6:7], -1
	ds_write2_b32 v66, v96, v80 offset0:104 offset1:136
	ds_write2_b32 v0, v97, v81 offset0:108 offset1:140
	s_waitcnt lgkmcnt(0)
	s_barrier
	s_cbranch_scc1 .LBB0_439
	s_cmp_gt_i32 s14, 14
	s_cbranch_scc0 .LBB0_436
	s_mov_b64 s[6:7], 0

.Lg588_loop:
	v_add_u32_e32 v136, s11, v134
	v_add_u32_e32 v137, s11, v135
	s_add_i32 s7, s7, 1
	s_add_u32 s73, s11, 0x6000
	s_cmp_lt_u32 s73, 0x12000
	s_cselect_b32 s73, s73, 0
	v_add_u32_e32 v138, s73, v132
	v_add_u32_e32 v139, s73, v133
	s_waitcnt lgkmcnt(0)
	v_mfma_f32_32x32x16_bf16 v[114:129], v[162:165], v[228:231], v[114:129]
	ds_read_b128 v[166:169], v136 offset:0
	ds_read_b128 v[232:235], v137 offset:0
	s_add_i32 s14, s7, 2
	s_lshl_b64 s[12:13], s[14:15], 14
	v_lshl_add_u64 v[244:245], v[154:155], 0, s[12:13]
	v_mfma_f32_32x32x16_bf16 v[98:113], v[162:165], v[236:239], v[98:113]
	ds_read_b128 v[240:243], v137 offset:2048
	ds_read_b128 v[208:211], v136 offset:2048
	s_add_u32 s12, s12, 0x1000
	s_addc_u32 s13, s13, 0
	v_lshl_add_u64 v[246:247], v[154:155], 0, s[12:13]
	v_mfma_f32_32x32x16_bf16 v[82:97], v[204:207], v[228:231], v[82:97]
	ds_read_b128 v[216:219], v136 offset:4096
	ds_read_b128 v[224:227], v136 offset:6144
	s_add_u32 s12, s12, 0x1000
	s_addc_u32 s13, s13, 0
	v_lshl_add_u64 v[248:249], v[154:155], 0, s[12:13]
	v_mfma_f32_32x32x16_bf16 v[66:81], v[204:207], v[236:239], v[66:81]
	s_add_u32 s12, s12, 0x1000
	s_addc_u32 s13, s13, 0
	v_lshl_add_u64 v[140:141], v[154:155], 0, s[12:13]
	v_mfma_f32_32x32x16_bf16 v[50:65], v[212:215], v[228:231], v[50:65]
	s_lshl_b64 s[12:13], s[14:15], 13
	v_lshl_add_u64 v[142:143], v[156:157], 0, s[12:13]
	v_mfma_f32_32x32x16_bf16 v[34:49], v[212:215], v[236:239], v[34:49]
	s_add_u32 s12, s12, 0x1000
	s_addc_u32 s13, s13, 0
	v_lshl_add_u64 v[144:145], v[156:157], 0, s[12:13]
	v_mfma_f32_32x32x16_bf16 v[18:33], v[220:223], v[228:231], v[18:33]
	v_mfma_f32_32x32x16_bf16 v[2:17], v[220:223], v[236:239], v[2:17]
	s_waitcnt vmcnt(6) lgkmcnt(0)
	s_barrier
	s_add_u32 m0, s11, s72
	v_mfma_f32_32x32x16_bf16 v[114:129], v[166:169], v[232:235], v[114:129]
	global_load_lds_dwordx4 v[244:245], off
	ds_read_b128 v[162:165], v138 offset:0
	ds_read_b128 v[228:231], v139 offset:0
	s_add_u32 m0, m0, 0x1000
	v_mfma_f32_32x32x16_bf16 v[98:113], v[166:169], v[240:243], v[98:113]
	global_load_lds_dwordx4 v[246:247], off
	ds_read_b128 v[236:239], v139 offset:2048
	ds_read_b128 v[204:207], v138 offset:2048
	s_add_u32 m0, m0, 0x1000
	v_mfma_f32_32x32x16_bf16 v[82:97], v[208:211], v[232:235], v[82:97]
	global_load_lds_dwordx4 v[248:249], off
	ds_read_b128 v[212:215], v138 offset:4096
	ds_read_b128 v[220:223], v138 offset:6144
	s_add_u32 m0, m0, 0x1000
	v_mfma_f32_32x32x16_bf16 v[66:81], v[208:211], v[240:243], v[66:81]
	global_load_lds_dwordx4 v[140:141], off
	s_add_u32 m0, m0, 0x1000
	v_mfma_f32_32x32x16_bf16 v[50:65], v[216:219], v[232:235], v[50:65]
	global_load_lds_dwordx4 v[142:143], off
	s_add_u32 m0, m0, 0x1000
	v_mfma_f32_32x32x16_bf16 v[34:49], v[216:219], v[240:243], v[34:49]
	global_load_lds_dwordx4 v[144:145], off
	v_mfma_f32_32x32x16_bf16 v[18:33], v[224:227], v[232:235], v[18:33]
	v_mfma_f32_32x32x16_bf16 v[2:17], v[224:227], v[240:243], v[2:17]
	s_mov_b32 s11, s73
	s_cmp_lg_u32 s7, 125
	s_cbranch_scc1 .Lg588_loop
	v_add_u32_e32 v136, s11, v134
	v_add_u32_e32 v137, s11, v135
	s_add_i32 s7, s7, 1
	s_add_u32 s73, s11, 0x6000
	s_cmp_lt_u32 s73, 0x12000
	s_cselect_b32 s73, s73, 0
	v_add_u32_e32 v138, s73, v132
	v_add_u32_e32 v139, s73, v133
	s_waitcnt lgkmcnt(0)
	v_mfma_f32_32x32x16_bf16 v[114:129], v[162:165], v[228:231], v[114:129]
	ds_read_b128 v[166:169], v136 offset:0
	ds_read_b128 v[232:235], v137 offset:0
	v_mfma_f32_32x32x16_bf16 v[98:113], v[162:165], v[236:239], v[98:113]
	ds_read_b128 v[240:243], v137 offset:2048
	ds_read_b128 v[208:211], v136 offset:2048
	v_mfma_f32_32x32x16_bf16 v[82:97], v[204:207], v[228:231], v[82:97]
	ds_read_b128 v[216:219], v136 offset:4096
	ds_read_b128 v[224:227], v136 offset:6144
	v_mfma_f32_32x32x16_bf16 v[66:81], v[204:207], v[236:239], v[66:81]
	v_mfma_f32_32x32x16_bf16 v[50:65], v[212:215], v[228:231], v[50:65]
	v_mfma_f32_32x32x16_bf16 v[34:49], v[212:215], v[236:239], v[34:49]
	v_mfma_f32_32x32x16_bf16 v[18:33], v[220:223], v[228:231], v[18:33]
	v_mfma_f32_32x32x16_bf16 v[2:17], v[220:223], v[236:239], v[2:17]
	s_waitcnt vmcnt(6) lgkmcnt(0)
	s_barrier
	v_mfma_f32_32x32x16_bf16 v[114:129], v[166:169], v[232:235], v[114:129]
	ds_read_b128 v[162:165], v138 offset:0
	ds_read_b128 v[228:231], v139 offset:0
	v_mfma_f32_32x32x16_bf16 v[98:113], v[166:169], v[240:243], v[98:113]
	ds_read_b128 v[236:239], v139 offset:2048
	ds_read_b128 v[204:207], v138 offset:2048
	v_mfma_f32_32x32x16_bf16 v[82:97], v[208:211], v[232:235], v[82:97]
	ds_read_b128 v[212:215], v138 offset:4096
	ds_read_b128 v[220:223], v138 offset:6144
	v_mfma_f32_32x32x16_bf16 v[66:81], v[208:211], v[240:243], v[66:81]
	v_mfma_f32_32x32x16_bf16 v[50:65], v[216:219], v[232:235], v[50:65]
	v_mfma_f32_32x32x16_bf16 v[34:49], v[216:219], v[240:243], v[34:49]
	v_mfma_f32_32x32x16_bf16 v[18:33], v[224:227], v[232:235], v[18:33]
	v_mfma_f32_32x32x16_bf16 v[2:17], v[224:227], v[240:243], v[2:17]
	s_mov_b32 s11, s73
	v_add_u32_e32 v136, s11, v134
	v_add_u32_e32 v137, s11, v135
	s_add_i32 s7, s7, 1
	s_add_u32 s73, s11, 0x6000
	s_cmp_lt_u32 s73, 0x12000
	s_cselect_b32 s73, s73, 0
	v_add_u32_e32 v138, s73, v132
	v_add_u32_e32 v139, s73, v133
	s_waitcnt lgkmcnt(0)
	v_mfma_f32_32x32x16_bf16 v[114:129], v[162:165], v[228:231], v[114:129]
	ds_read_b128 v[166:169], v136 offset:0
	ds_read_b128 v[232:235], v137 offset:0
	v_mfma_f32_32x32x16_bf16 v[98:113], v[162:165], v[236:239], v[98:113]
	ds_read_b128 v[240:243], v137 offset:2048
	ds_read_b128 v[208:211], v136 offset:2048
	v_mfma_f32_32x32x16_bf16 v[82:97], v[204:207], v[228:231], v[82:97]
	ds_read_b128 v[216:219], v136 offset:4096
	ds_read_b128 v[224:227], v136 offset:6144
	v_mfma_f32_32x32x16_bf16 v[66:81], v[204:207], v[236:239], v[66:81]
	v_mfma_f32_32x32x16_bf16 v[50:65], v[212:215], v[228:231], v[50:65]
	v_mfma_f32_32x32x16_bf16 v[34:49], v[212:215], v[236:239], v[34:49]
	v_mfma_f32_32x32x16_bf16 v[18:33], v[220:223], v[228:231], v[18:33]
	v_mfma_f32_32x32x16_bf16 v[2:17], v[220:223], v[236:239], v[2:17]
	s_waitcnt vmcnt(0) lgkmcnt(0)
	s_barrier
	v_mfma_f32_32x32x16_bf16 v[114:129], v[166:169], v[232:235], v[114:129]
	ds_read_b128 v[162:165], v138 offset:0
	ds_read_b128 v[228:231], v139 offset:0
	v_mfma_f32_32x32x16_bf16 v[98:113], v[166:169], v[240:243], v[98:113]
	ds_read_b128 v[236:239], v139 offset:2048
	ds_read_b128 v[204:207], v138 offset:2048
	v_mfma_f32_32x32x16_bf16 v[82:97], v[208:211], v[232:235], v[82:97]
	ds_read_b128 v[212:215], v138 offset:4096
	ds_read_b128 v[220:223], v138 offset:6144
	v_mfma_f32_32x32x16_bf16 v[66:81], v[208:211], v[240:243], v[66:81]
	v_mfma_f32_32x32x16_bf16 v[50:65], v[216:219], v[232:235], v[50:65]
	v_mfma_f32_32x32x16_bf16 v[34:49], v[216:219], v[240:243], v[34:49]
	v_mfma_f32_32x32x16_bf16 v[18:33], v[224:227], v[232:235], v[18:33]
	v_mfma_f32_32x32x16_bf16 v[2:17], v[224:227], v[240:243], v[2:17]
	s_mov_b32 s11, s73
	v_add_u32_e32 v136, s11, v134
	v_add_u32_e32 v137, s11, v135
	s_add_i32 s7, s7, 1
	s_waitcnt lgkmcnt(0)
	v_mfma_f32_32x32x16_bf16 v[114:129], v[162:165], v[228:231], v[114:129]
	ds_read_b128 v[166:169], v136 offset:0
	ds_read_b128 v[232:235], v137 offset:0
	v_mfma_f32_32x32x16_bf16 v[98:113], v[162:165], v[236:239], v[98:113]
	ds_read_b128 v[240:243], v137 offset:2048
	ds_read_b128 v[208:211], v136 offset:2048
	v_mfma_f32_32x32x16_bf16 v[82:97], v[204:207], v[228:231], v[82:97]
	ds_read_b128 v[216:219], v136 offset:4096
	ds_read_b128 v[224:227], v136 offset:6144
	v_mfma_f32_32x32x16_bf16 v[66:81], v[204:207], v[236:239], v[66:81]
	v_mfma_f32_32x32x16_bf16 v[50:65], v[212:215], v[228:231], v[50:65]
	v_mfma_f32_32x32x16_bf16 v[34:49], v[212:215], v[236:239], v[34:49]
	v_mfma_f32_32x32x16_bf16 v[18:33], v[220:223], v[228:231], v[18:33]
	v_mfma_f32_32x32x16_bf16 v[2:17], v[220:223], v[236:239], v[2:17]
	s_waitcnt lgkmcnt(0)
	v_mfma_f32_32x32x16_bf16 v[114:129], v[166:169], v[232:235], v[114:129]
	v_mfma_f32_32x32x16_bf16 v[98:113], v[166:169], v[240:243], v[98:113]
	v_mfma_f32_32x32x16_bf16 v[82:97], v[208:211], v[232:235], v[82:97]
	v_mfma_f32_32x32x16_bf16 v[66:81], v[208:211], v[240:243], v[66:81]
	v_mfma_f32_32x32x16_bf16 v[50:65], v[216:219], v[232:235], v[50:65]
	v_mfma_f32_32x32x16_bf16 v[34:49], v[216:219], v[240:243], v[34:49]
	v_mfma_f32_32x32x16_bf16 v[18:33], v[224:227], v[232:235], v[18:33]
	v_mfma_f32_32x32x16_bf16 v[2:17], v[224:227], v[240:243], v[2:17]
	s_mov_b32 s14, 127
	s_lshl_b64 s[12:13], s[14:15], 13
	s_movk_i32 s11, 0x7800
	s_movk_i32 s72, 0x6000
	s_mov_b32 s73, 0xc000
	v_mov_b32_e32 v0, v171
	s_barrier
	s_movk_i32 s0, 0x210
	s_waitcnt vmcnt(4)
	v_lshrrev_b32_e32 v130, 1, v0
	v_and_b32_e32 v130, 0xfffffc0, v130
	v_lshrrev_b32_e32 v131, 3, v0
	v_and_or_b32 v130, v131, 4, v130
	v_and_b32_e32 v0, 0x5f, v0
	v_mul_lo_u32 v130, v130, s0
	v_lshl_add_u32 v0, v0, 2, v130
	s_barrier
	ds_write2_b32 v0, v114, v98 offset1:32
	ds_write2_b32 v0, v115, v99 offset0:132 offset1:164
	v_add_u32_e32 v98, 0x400, v0
	ds_write2_b32 v98, v116, v100 offset0:8 offset1:40
	ds_write2_b32 v98, v117, v101 offset0:140 offset1:172
	v_add_u32_e32 v98, 0x1000, v0
	ds_write2_b32 v98, v118, v102 offset0:32 offset1:64
	ds_write2_b32 v98, v119, v103 offset0:164 offset1:196
	v_add_u32_e32 v98, 0x1400, v0
	ds_write2_b32 v98, v120, v104 offset0:40 offset1:72
	ds_write2_b32 v98, v121, v105 offset0:172 offset1:204
	v_add_u32_e32 v98, 0x2000, v0
	ds_write2_b32 v98, v122, v106 offset0:64 offset1:96
	ds_write2_b32 v98, v123, v107 offset0:196 offset1:228
	v_add_u32_e32 v98, 0x2400, v0
	ds_write2_b32 v98, v124, v108 offset0:72 offset1:104
	ds_write2_b32 v98, v125, v109 offset0:204 offset1:236
	v_add_u32_e32 v98, 0x3000, v0
	ds_write2_b32 v98, v126, v110 offset0:96 offset1:128
	v_add_u32_e32 v98, 0x3200, v0
	ds_write2_b32 v98, v127, v111 offset0:100 offset1:132
	v_add_u32_e32 v98, 0x3400, v0
	ds_write2_b32 v98, v128, v112 offset0:104 offset1:136
	v_add_u32_e32 v98, 0x3600, v0
	ds_write2_b32 v98, v129, v113 offset0:108 offset1:140
	v_add_u32_e32 v98, 0x4000, v0
	ds_write2_b32 v98, v82, v66 offset0:128 offset1:160
	v_add_u32_e32 v66, 0x4400, v0
	ds_write2_b32 v66, v83, v67 offset0:4 offset1:36
	ds_write2_b32 v66, v84, v68 offset0:136 offset1:168
	v_add_u32_e32 v66, 0x4800, v0
	ds_write2_b32 v66, v85, v69 offset0:12 offset1:44
	v_add_u32_e32 v66, 0x5000, v0
	s_lshl_b32 s10, s10, 8
	ds_write2_b32 v66, v86, v70 offset0:160 offset1:192
	v_add_u32_e32 v66, 0x5400, v0
	s_lshl_b32 s11, s6, 7
	ds_write2_b32 v66, v87, v71 offset0:36 offset1:68
	ds_write2_b32 v66, v88, v72 offset0:168 offset1:200
	v_add_u32_e32 v66, 0x5800, v0
	s_add_i32 s6, s10, 0xffffe000
	ds_write2_b32 v66, v89, v73 offset0:44 offset1:76
	v_add_u32_e32 v66, 0x6000, v0
	s_lshr_b32 s6, s6, 12
	ds_write2_b32 v66, v90, v74 offset0:192 offset1:224
	v_add_u32_e32 v66, 0x6400, v0
	s_mulk_i32 s6, 0x1800
	ds_write2_b32 v66, v91, v75 offset0:68 offset1:100
	ds_write2_b32 v66, v92, v76 offset0:200 offset1:232
	v_add_u32_e32 v66, 0x6800, v0
	s_addk_i32 s6, 0x1800
	ds_write2_b32 v66, v93, v77 offset0:76 offset1:108
	v_add_u32_e32 v66, 0x7200, v0
	s_cmp_gt_u32 s9, 31
	ds_write2_b32 v66, v94, v78 offset0:96 offset1:128
	v_add_u32_e32 v66, 0x7400, v0
	s_cselect_b32 s14, s6, 0
	ds_write2_b32 v66, v95, v79 offset0:100 offset1:132
	v_add_u32_e32 v66, 0x7600, v0
	v_add_u32_e32 v0, 0x7800, v0
	v_mov_b32_e32 v84, v171
	s_lshl_b64 s[6:7], s[14:15], 2
	ds_write2_b32 v66, v96, v80 offset0:104 offset1:136
	ds_write2_b32 v0, v97, v81 offset0:108 offset1:140
	s_waitcnt lgkmcnt(0)
	s_barrier
	s_add_u32 s6, s61, s6
	v_lshlrev_b32_e32 v0, 3, v84
	v_and_b32_e32 v0, 0x78, v0
	s_addc_u32 s7, s53, s7
	v_or_b32_e32 v0, s11, v0
	s_add_u32 s6, s6, 0x1d645000
	s_addc_u32 s7, s7, 0
	v_lshlrev_b64 v[82:83], 2, v[0:1]
	v_lshl_add_u64 v[70:71], s[6:7], 0, v[82:83]
	v_lshl_add_u64 v[78:79], s[4:5], 0, v[82:83]
	global_load_dwordx4 v[66:69], v[70:71], off offset:16
	s_nop 0
	global_load_dwordx4 v[70:73], v[70:71], off
	s_nop 0
	global_load_dwordx4 v[74:77], v[78:79], off offset:16
	s_nop 0
	global_load_dwordx4 v[78:81], v[78:79], off
	v_ashrrev_i32_e32 v0, 4, v84
	v_mul_lo_u32 v85, v0, s0
	v_and_b32_e32 v84, 15, v84
	s_mov_b32 s9, 0
	v_lshl_add_u64 v[82:83], s[56:57], 0, v[82:83]
	v_lshl_add_u32 v84, v84, 5, v85
	v_lshlrev_b32_e32 v85, 1, v0
